# v65 + hand-scheduled silu (c_z, b_z) and paired (a_b*silu(a_z), c_val*sigmoid(c_gate)) proj epilogue variants
# baseline (speedup 1.0000x reference)
; __device__ __forceinline__ u32x4 pack8(f32x4 a, f32x4 b) { u32x4 w; w.x = cvt_pk_bf16(a[0], a[1]); w.y = cvt_pk_bf16(a[2], a[3]); w.z = cvt_pk_bf16(b[0], b[1]); w.w = cvt_pk_bf16(b[2], b[3]); return w; }
; __device__ __forceinline__ float sigmoid_f(float x) { return __builtin_amdgcn_rcpf(1.0f + __builtin_amdgcn_exp2f(-1.4426950409f * x)); }
; __device__ __forceinline__ float silu_f(float x) { return x * sigmoid_f(x); }
;     template <int ACT> __device__ __forceinline__ void body(f32x4 (&acc)[2][2][4][2], const Unit& u, int wr, int wc, int fr, int fq, int obase, const float (&rsv)[2][4]) const {
;         EPI_ROWS_BEGIN
;             const float rs = rsv[ai][m];
; #pragma unroll
;             for (int bj = 0; bj < 2; ++bj) { const int col = obase + bj * 128 + wc * 32 + 8 * fq;
;                 f32x4 v0 = acc[ai][bj][m][0] * rs, v1 = acc[ai][bj][m][1] * rs;
;                 if (ACT == 1) {
; #pragma unroll
;                     for (int j = 0; j < 4; ++j) { v0[j] = silu_f(v0[j]); v1[j] = silu_f(v1[j]); } }
;                 if (ACT == 2) {
; #pragma unroll
;                     for (int j = 0; j < 4; ++j) { v0[j] = sigmoid_f(v0[j]); v1[j] = sigmoid_f(v1[j]); } }
;                 __builtin_nontemporal_store(pack8(v0, v1), (u32x4*)(P + (size_t)row * NCO + col));
;             }
;         EPI_END
.LBB0_206:
	s_andn2_b64 vcc, exec, s[4:5]
	s_cbranch_vccnz .LBB0_208
	s_lshl_b32 s4, s52, 8
	s_add_i32 s4, s4, s28
	s_mov_b32 s98, 0xbfb8aa3b
	v_lshl_add_u32 v228, v143, 3, s4
	v_lshlrev_b32_e32 v228, 1, v228
	v_ashrrev_i32_e32 v229, 31, v228
	v_lshl_add_u64 v[232:233], s[68:69], 0, v[228:229]
	v_mad_i64_i32 v[234:235], s[4:5], v154, s33, v[232:233]
	v_pk_mul_f32 v[126:127], v[126:127], v[158:159] op_sel_hi:[1,0]
	v_pk_mul_f32 v[128:129], v[128:129], v[158:159] op_sel_hi:[1,0]
	v_pk_mul_f32 v[122:123], v[122:123], v[158:159] op_sel_hi:[1,0]
	v_pk_mul_f32 v[124:125], v[124:125], v[158:159] op_sel_hi:[1,0]
	v_pk_mul_f32 v[168:169], v[126:127], s[98:99] op_sel_hi:[1,0]
	v_pk_mul_f32 v[170:171], v[128:129], s[98:99] op_sel_hi:[1,0]
	v_pk_mul_f32 v[172:173], v[122:123], s[98:99] op_sel_hi:[1,0]
	v_pk_mul_f32 v[174:175], v[124:125], s[98:99] op_sel_hi:[1,0]
	v_exp_f32_e32 v168, v168
	v_exp_f32_e32 v169, v169
	v_exp_f32_e32 v170, v170
	v_exp_f32_e32 v171, v171
	v_exp_f32_e32 v172, v172
	v_exp_f32_e32 v173, v173
	v_exp_f32_e32 v174, v174
	v_exp_f32_e32 v175, v175
	v_pk_add_f32 v[168:169], v[168:169], 1.0 op_sel_hi:[1,0]
	v_pk_add_f32 v[170:171], v[170:171], 1.0 op_sel_hi:[1,0]
	v_pk_add_f32 v[172:173], v[172:173], 1.0 op_sel_hi:[1,0]
	v_pk_add_f32 v[174:175], v[174:175], 1.0 op_sel_hi:[1,0]
	v_rcp_f32_e32 v168, v168
	v_rcp_f32_e32 v169, v169
	v_rcp_f32_e32 v170, v170
	v_rcp_f32_e32 v171, v171
	v_rcp_f32_e32 v172, v172
	v_rcp_f32_e32 v173, v173
	v_rcp_f32_e32 v174, v174
	v_rcp_f32_e32 v175, v175
	v_pk_mul_f32 v[126:127], v[126:127], v[168:169]
	v_pk_mul_f32 v[128:129], v[128:129], v[170:171]
	v_pk_mul_f32 v[122:123], v[122:123], v[172:173]
	v_pk_mul_f32 v[124:125], v[124:125], v[174:175]
	v_cvt_pk_bf16_f32 v176, v126, v127
	v_cvt_pk_bf16_f32 v177, v128, v129
	v_cvt_pk_bf16_f32 v178, v122, v123
	v_cvt_pk_bf16_f32 v179, v124, v125
	global_store_dwordx4 v[234:235], v[176:179], off nt
	v_pk_mul_f32 v[118:119], v[118:119], v[158:159] op_sel_hi:[1,0]
	v_pk_mul_f32 v[120:121], v[120:121], v[158:159] op_sel_hi:[1,0]
	v_pk_mul_f32 v[110:111], v[110:111], v[158:159] op_sel_hi:[1,0]
	v_pk_mul_f32 v[112:113], v[112:113], v[158:159] op_sel_hi:[1,0]
	v_pk_mul_f32 v[168:169], v[118:119], s[98:99] op_sel_hi:[1,0]
	v_pk_mul_f32 v[170:171], v[120:121], s[98:99] op_sel_hi:[1,0]
	v_pk_mul_f32 v[172:173], v[110:111], s[98:99] op_sel_hi:[1,0]
	v_pk_mul_f32 v[174:175], v[112:113], s[98:99] op_sel_hi:[1,0]
	v_exp_f32_e32 v168, v168
	v_exp_f32_e32 v169, v169
	v_exp_f32_e32 v170, v170
	v_exp_f32_e32 v171, v171
	v_exp_f32_e32 v172, v172
	v_exp_f32_e32 v173, v173
	v_exp_f32_e32 v174, v174
	v_exp_f32_e32 v175, v175
	v_pk_add_f32 v[168:169], v[168:169], 1.0 op_sel_hi:[1,0]
	v_pk_add_f32 v[170:171], v[170:171], 1.0 op_sel_hi:[1,0]
	v_pk_add_f32 v[172:173], v[172:173], 1.0 op_sel_hi:[1,0]
	v_pk_add_f32 v[174:175], v[174:175], 1.0 op_sel_hi:[1,0]
	v_rcp_f32_e32 v168, v168
	v_rcp_f32_e32 v169, v169
	v_rcp_f32_e32 v170, v170
	v_rcp_f32_e32 v171, v171
	v_rcp_f32_e32 v172, v172
	v_rcp_f32_e32 v173, v173
	v_rcp_f32_e32 v174, v174
	v_rcp_f32_e32 v175, v175
	v_pk_mul_f32 v[118:119], v[118:119], v[168:169]
	v_pk_mul_f32 v[120:121], v[120:121], v[170:171]
	v_pk_mul_f32 v[110:111], v[110:111], v[172:173]
	v_pk_mul_f32 v[112:113], v[112:113], v[174:175]
	v_cvt_pk_bf16_f32 v180, v118, v119
	v_cvt_pk_bf16_f32 v181, v120, v121
	v_cvt_pk_bf16_f32 v182, v110, v111
	v_cvt_pk_bf16_f32 v183, v112, v113
	global_store_dwordx4 v[234:235], v[180:183], off offset:256 nt
	v_mad_i64_i32 v[236:237], s[4:5], v209, s33, v[232:233]
	v_pk_mul_f32 v[114:115], v[114:115], v[156:157] op_sel_hi:[1,0]
	v_pk_mul_f32 v[116:117], v[116:117], v[156:157] op_sel_hi:[1,0]
	v_pk_mul_f32 v[106:107], v[106:107], v[156:157] op_sel_hi:[1,0]
	v_pk_mul_f32 v[108:109], v[108:109], v[156:157] op_sel_hi:[1,0]
	v_pk_mul_f32 v[168:169], v[114:115], s[98:99] op_sel_hi:[1,0]
	v_pk_mul_f32 v[170:171], v[116:117], s[98:99] op_sel_hi:[1,0]
	v_pk_mul_f32 v[172:173], v[106:107], s[98:99] op_sel_hi:[1,0]
	v_pk_mul_f32 v[174:175], v[108:109], s[98:99] op_sel_hi:[1,0]
	v_exp_f32_e32 v168, v168
	v_exp_f32_e32 v169, v169
	v_exp_f32_e32 v170, v170
	v_exp_f32_e32 v171, v171
	v_exp_f32_e32 v172, v172
	v_exp_f32_e32 v173, v173
	v_exp_f32_e32 v174, v174
	v_exp_f32_e32 v175, v175
	v_pk_add_f32 v[168:169], v[168:169], 1.0 op_sel_hi:[1,0]
	v_pk_add_f32 v[170:171], v[170:171], 1.0 op_sel_hi:[1,0]
	v_pk_add_f32 v[172:173], v[172:173], 1.0 op_sel_hi:[1,0]
	v_pk_add_f32 v[174:175], v[174:175], 1.0 op_sel_hi:[1,0]
	v_rcp_f32_e32 v168, v168
	v_rcp_f32_e32 v169, v169
	v_rcp_f32_e32 v170, v170
	v_rcp_f32_e32 v171, v171
	v_rcp_f32_e32 v172, v172
	v_rcp_f32_e32 v173, v173
	v_rcp_f32_e32 v174, v174
	v_rcp_f32_e32 v175, v175
	v_pk_mul_f32 v[114:115], v[114:115], v[168:169]
	v_pk_mul_f32 v[116:117], v[116:117], v[170:171]
	v_pk_mul_f32 v[106:107], v[106:107], v[172:173]
	v_pk_mul_f32 v[108:109], v[108:109], v[174:175]
	v_cvt_pk_bf16_f32 v176, v114, v115
	v_cvt_pk_bf16_f32 v177, v116, v117
	v_cvt_pk_bf16_f32 v178, v106, v107
	v_cvt_pk_bf16_f32 v179, v108, v109
	global_store_dwordx4 v[236:237], v[176:179], off nt
	v_pk_mul_f32 v[98:99], v[98:99], v[156:157] op_sel_hi:[1,0]
	v_pk_mul_f32 v[100:101], v[100:101], v[156:157] op_sel_hi:[1,0]
	v_pk_mul_f32 v[90:91], v[90:91], v[156:157] op_sel_hi:[1,0]
	v_pk_mul_f32 v[92:93], v[92:93], v[156:157] op_sel_hi:[1,0]
	v_pk_mul_f32 v[168:169], v[98:99], s[98:99] op_sel_hi:[1,0]
	v_pk_mul_f32 v[170:171], v[100:101], s[98:99] op_sel_hi:[1,0]
	v_pk_mul_f32 v[172:173], v[90:91], s[98:99] op_sel_hi:[1,0]
	v_pk_mul_f32 v[174:175], v[92:93], s[98:99] op_sel_hi:[1,0]
	v_exp_f32_e32 v168, v168
	v_exp_f32_e32 v169, v169
	v_exp_f32_e32 v170, v170
; __device__ __forceinline__ u32x4 pack8(f32x4 a, f32x4 b) { u32x4 w; w.x = cvt_pk_bf16(a[0], a[1]); w.y = cvt_pk_bf16(a[2], a[3]); w.z = cvt_pk_bf16(b[0], b[1]); w.w = cvt_pk_bf16(b[2], b[3]); return w; }
; __device__ __forceinline__ float sigmoid_f(float x) { return __builtin_amdgcn_rcpf(1.0f + __builtin_amdgcn_exp2f(-1.4426950409f * x)); }
; __device__ __forceinline__ float silu_f(float x) { return x * sigmoid_f(x); }
;     template <int ACT> __device__ __forceinline__ void body(f32x4 (&acc)[2][2][4][2], const Unit& u, int wr, int wc, int fr, int fq, int obase, const float (&rsv)[2][4]) const {
;     ...
;             for (int bj = 0; bj < 2; ++bj) { const int col = obase + bj * 128 + wc * 32 + 8 * fq;
;                 f32x4 v0 = acc[ai][bj][m][0] * rs, v1 = acc[ai][bj][m][1] * rs;
;                 if (ACT == 1) {
; #pragma unroll
;                     for (int j = 0; j < 4; ++j) { v0[j] = silu_f(v0[j]); v1[j] = silu_f(v1[j]); } }
;                 if (ACT == 2) {
; #pragma unroll
;                     for (int j = 0; j < 4; ++j) { v0[j] = sigmoid_f(v0[j]); v1[j] = sigmoid_f(v1[j]); } }
;                 __builtin_nontemporal_store(pack8(v0, v1), (u32x4*)(P + (size_t)row * NCO + col));
;             }
	v_exp_f32_e32 v171, v171
	v_exp_f32_e32 v172, v172
	v_exp_f32_e32 v173, v173
	v_exp_f32_e32 v174, v174
	v_exp_f32_e32 v175, v175
	v_pk_add_f32 v[168:169], v[168:169], 1.0 op_sel_hi:[1,0]
	v_pk_add_f32 v[170:171], v[170:171], 1.0 op_sel_hi:[1,0]
	v_pk_add_f32 v[172:173], v[172:173], 1.0 op_sel_hi:[1,0]
	v_pk_add_f32 v[174:175], v[174:175], 1.0 op_sel_hi:[1,0]
	v_rcp_f32_e32 v168, v168
	v_rcp_f32_e32 v169, v169
	v_rcp_f32_e32 v170, v170
	v_rcp_f32_e32 v171, v171
	v_rcp_f32_e32 v172, v172
	v_rcp_f32_e32 v173, v173
	v_rcp_f32_e32 v174, v174
	v_rcp_f32_e32 v175, v175
	v_pk_mul_f32 v[98:99], v[98:99], v[168:169]
	v_pk_mul_f32 v[100:101], v[100:101], v[170:171]
	v_pk_mul_f32 v[90:91], v[90:91], v[172:173]
	v_pk_mul_f32 v[92:93], v[92:93], v[174:175]
	v_cvt_pk_bf16_f32 v180, v98, v99
	v_cvt_pk_bf16_f32 v181, v100, v101
	v_cvt_pk_bf16_f32 v182, v90, v91
	v_cvt_pk_bf16_f32 v183, v92, v93
	global_store_dwordx4 v[236:237], v[180:183], off offset:256 nt
	v_mad_i64_i32 v[234:235], s[4:5], v208, s33, v[232:233]
	v_pk_mul_f32 v[102:103], v[102:103], v[152:153] op_sel_hi:[1,0]
	v_pk_mul_f32 v[104:105], v[104:105], v[152:153] op_sel_hi:[1,0]
	v_pk_mul_f32 v[94:95], v[94:95], v[152:153] op_sel_hi:[1,0]
	v_pk_mul_f32 v[96:97], v[96:97], v[152:153] op_sel_hi:[1,0]
	v_pk_mul_f32 v[168:169], v[102:103], s[98:99] op_sel_hi:[1,0]
	v_pk_mul_f32 v[170:171], v[104:105], s[98:99] op_sel_hi:[1,0]
	v_pk_mul_f32 v[172:173], v[94:95], s[98:99] op_sel_hi:[1,0]
	v_pk_mul_f32 v[174:175], v[96:97], s[98:99] op_sel_hi:[1,0]
	v_exp_f32_e32 v168, v168
	v_exp_f32_e32 v169, v169
	v_exp_f32_e32 v170, v170
	v_exp_f32_e32 v171, v171
	v_exp_f32_e32 v172, v172
	v_exp_f32_e32 v173, v173
	v_exp_f32_e32 v174, v174
	v_exp_f32_e32 v175, v175
	v_pk_add_f32 v[168:169], v[168:169], 1.0 op_sel_hi:[1,0]
	v_pk_add_f32 v[170:171], v[170:171], 1.0 op_sel_hi:[1,0]
	v_pk_add_f32 v[172:173], v[172:173], 1.0 op_sel_hi:[1,0]
	v_pk_add_f32 v[174:175], v[174:175], 1.0 op_sel_hi:[1,0]
	v_rcp_f32_e32 v168, v168
	v_rcp_f32_e32 v169, v169
	v_rcp_f32_e32 v170, v170
	v_rcp_f32_e32 v171, v171
	v_rcp_f32_e32 v172, v172
	v_rcp_f32_e32 v173, v173
	v_rcp_f32_e32 v174, v174
	v_rcp_f32_e32 v175, v175
	v_pk_mul_f32 v[102:103], v[102:103], v[168:169]
	v_pk_mul_f32 v[104:105], v[104:105], v[170:171]
	v_pk_mul_f32 v[94:95], v[94:95], v[172:173]
	v_pk_mul_f32 v[96:97], v[96:97], v[174:175]
	v_cvt_pk_bf16_f32 v176, v102, v103
	v_cvt_pk_bf16_f32 v177, v104, v105
	v_cvt_pk_bf16_f32 v178, v94, v95
	v_cvt_pk_bf16_f32 v179, v96, v97
	global_store_dwordx4 v[234:235], v[176:179], off nt
	v_pk_mul_f32 v[82:83], v[82:83], v[152:153] op_sel_hi:[1,0]
	v_pk_mul_f32 v[84:85], v[84:85], v[152:153] op_sel_hi:[1,0]
	v_pk_mul_f32 v[74:75], v[74:75], v[152:153] op_sel_hi:[1,0]
	v_pk_mul_f32 v[76:77], v[76:77], v[152:153] op_sel_hi:[1,0]
	v_pk_mul_f32 v[168:169], v[82:83], s[98:99] op_sel_hi:[1,0]
	v_pk_mul_f32 v[170:171], v[84:85], s[98:99] op_sel_hi:[1,0]
	v_pk_mul_f32 v[172:173], v[74:75], s[98:99] op_sel_hi:[1,0]
	v_pk_mul_f32 v[174:175], v[76:77], s[98:99] op_sel_hi:[1,0]
	v_exp_f32_e32 v168, v168
	v_exp_f32_e32 v169, v169
	v_exp_f32_e32 v170, v170
	v_exp_f32_e32 v171, v171
	v_exp_f32_e32 v172, v172
	v_exp_f32_e32 v173, v173
	v_exp_f32_e32 v174, v174
	v_exp_f32_e32 v175, v175
	v_pk_add_f32 v[168:169], v[168:169], 1.0 op_sel_hi:[1,0]
	v_pk_add_f32 v[170:171], v[170:171], 1.0 op_sel_hi:[1,0]
	v_pk_add_f32 v[172:173], v[172:173], 1.0 op_sel_hi:[1,0]
	v_pk_add_f32 v[174:175], v[174:175], 1.0 op_sel_hi:[1,0]
	v_rcp_f32_e32 v168, v168
	v_rcp_f32_e32 v169, v169
	v_rcp_f32_e32 v170, v170
	v_rcp_f32_e32 v171, v171
	v_rcp_f32_e32 v172, v172
	v_rcp_f32_e32 v173, v173
	v_rcp_f32_e32 v174, v174
	v_rcp_f32_e32 v175, v175
	v_pk_mul_f32 v[82:83], v[82:83], v[168:169]
	v_pk_mul_f32 v[84:85], v[84:85], v[170:171]
	v_pk_mul_f32 v[74:75], v[74:75], v[172:173]
	v_pk_mul_f32 v[76:77], v[76:77], v[174:175]
	v_cvt_pk_bf16_f32 v180, v82, v83
	v_cvt_pk_bf16_f32 v181, v84, v85
	v_cvt_pk_bf16_f32 v182, v74, v75
	v_cvt_pk_bf16_f32 v183, v76, v77
	global_store_dwordx4 v[234:235], v[180:183], off offset:256 nt
	v_mad_i64_i32 v[236:237], s[4:5], v157, s33, v[232:233]
	v_pk_mul_f32 v[86:87], v[86:87], v[150:151] op_sel_hi:[1,0]
	v_pk_mul_f32 v[88:89], v[88:89], v[150:151] op_sel_hi:[1,0]
	v_pk_mul_f32 v[78:79], v[78:79], v[150:151] op_sel_hi:[1,0]
	v_pk_mul_f32 v[80:81], v[80:81], v[150:151] op_sel_hi:[1,0]
	v_pk_mul_f32 v[168:169], v[86:87], s[98:99] op_sel_hi:[1,0]
	v_pk_mul_f32 v[170:171], v[88:89], s[98:99] op_sel_hi:[1,0]
	v_pk_mul_f32 v[172:173], v[78:79], s[98:99] op_sel_hi:[1,0]
	v_pk_mul_f32 v[174:175], v[80:81], s[98:99] op_sel_hi:[1,0]
	v_exp_f32_e32 v168, v168
	v_exp_f32_e32 v169, v169
	v_exp_f32_e32 v170, v170
	v_exp_f32_e32 v171, v171
	v_exp_f32_e32 v172, v172
	v_exp_f32_e32 v173, v173
	v_exp_f32_e32 v174, v174
	v_exp_f32_e32 v175, v175
	v_pk_add_f32 v[168:169], v[168:169], 1.0 op_sel_hi:[1,0]
	v_pk_add_f32 v[170:171], v[170:171], 1.0 op_sel_hi:[1,0]
	v_pk_add_f32 v[172:173], v[172:173], 1.0 op_sel_hi:[1,0]
	v_pk_add_f32 v[174:175], v[174:175], 1.0 op_sel_hi:[1,0]
	v_rcp_f32_e32 v168, v168
	v_rcp_f32_e32 v169, v169
	v_rcp_f32_e32 v170, v170
	v_rcp_f32_e32 v171, v171
	v_rcp_f32_e32 v172, v172
	v_rcp_f32_e32 v173, v173
	v_rcp_f32_e32 v174, v174
	v_rcp_f32_e32 v175, v175
	v_pk_mul_f32 v[86:87], v[86:87], v[168:169]
	v_pk_mul_f32 v[88:89], v[88:89], v[170:171]
	v_pk_mul_f32 v[78:79], v[78:79], v[172:173]
	v_pk_mul_f32 v[80:81], v[80:81], v[174:175]
	v_cvt_pk_bf16_f32 v176, v86, v87
	v_cvt_pk_bf16_f32 v177, v88, v89
	v_cvt_pk_bf16_f32 v178, v78, v79
	v_cvt_pk_bf16_f32 v179, v80, v81
	global_store_dwordx4 v[236:237], v[176:179], off nt
; __device__ __forceinline__ u32x4 pack8(f32x4 a, f32x4 b) { u32x4 w; w.x = cvt_pk_bf16(a[0], a[1]); w.y = cvt_pk_bf16(a[2], a[3]); w.z = cvt_pk_bf16(b[0], b[1]); w.w = cvt_pk_bf16(b[2], b[3]); return w; }
; __device__ __forceinline__ float sigmoid_f(float x) { return __builtin_amdgcn_rcpf(1.0f + __builtin_amdgcn_exp2f(-1.4426950409f * x)); }
; __device__ __forceinline__ float silu_f(float x) { return x * sigmoid_f(x); }
;     template <int ACT> __device__ __forceinline__ void body(f32x4 (&acc)[2][2][4][2], const Unit& u, int wr, int wc, int fr, int fq, int obase, const float (&rsv)[2][4]) const {
;     ...
;             for (int bj = 0; bj < 2; ++bj) { const int col = obase + bj * 128 + wc * 32 + 8 * fq;
;                 f32x4 v0 = acc[ai][bj][m][0] * rs, v1 = acc[ai][bj][m][1] * rs;
;                 if (ACT == 1) {
; #pragma unroll
;                     for (int j = 0; j < 4; ++j) { v0[j] = silu_f(v0[j]); v1[j] = silu_f(v1[j]); } }
;                 if (ACT == 2) {
; #pragma unroll
;                     for (int j = 0; j < 4; ++j) { v0[j] = sigmoid_f(v0[j]); v1[j] = sigmoid_f(v1[j]); } }
;                 __builtin_nontemporal_store(pack8(v0, v1), (u32x4*)(P + (size_t)row * NCO + col));
;             }
	v_pk_mul_f32 v[70:71], v[70:71], v[150:151] op_sel_hi:[1,0]
	v_pk_mul_f32 v[72:73], v[72:73], v[150:151] op_sel_hi:[1,0]
	v_pk_mul_f32 v[66:67], v[66:67], v[150:151] op_sel_hi:[1,0]
	v_pk_mul_f32 v[68:69], v[68:69], v[150:151] op_sel_hi:[1,0]
	v_pk_mul_f32 v[168:169], v[70:71], s[98:99] op_sel_hi:[1,0]
	v_pk_mul_f32 v[170:171], v[72:73], s[98:99] op_sel_hi:[1,0]
	v_pk_mul_f32 v[172:173], v[66:67], s[98:99] op_sel_hi:[1,0]
	v_pk_mul_f32 v[174:175], v[68:69], s[98:99] op_sel_hi:[1,0]
	v_exp_f32_e32 v168, v168
	v_exp_f32_e32 v169, v169
	v_exp_f32_e32 v170, v170
	v_exp_f32_e32 v171, v171
	v_exp_f32_e32 v172, v172
	v_exp_f32_e32 v173, v173
	v_exp_f32_e32 v174, v174
	v_exp_f32_e32 v175, v175
	v_pk_add_f32 v[168:169], v[168:169], 1.0 op_sel_hi:[1,0]
	v_pk_add_f32 v[170:171], v[170:171], 1.0 op_sel_hi:[1,0]
	v_pk_add_f32 v[172:173], v[172:173], 1.0 op_sel_hi:[1,0]
	v_pk_add_f32 v[174:175], v[174:175], 1.0 op_sel_hi:[1,0]
	v_rcp_f32_e32 v168, v168
	v_rcp_f32_e32 v169, v169
	v_rcp_f32_e32 v170, v170
	v_rcp_f32_e32 v171, v171
	v_rcp_f32_e32 v172, v172
	v_rcp_f32_e32 v173, v173
	v_rcp_f32_e32 v174, v174
	v_rcp_f32_e32 v175, v175
	v_pk_mul_f32 v[70:71], v[70:71], v[168:169]
	v_pk_mul_f32 v[72:73], v[72:73], v[170:171]
	v_pk_mul_f32 v[66:67], v[66:67], v[172:173]
	v_pk_mul_f32 v[68:69], v[68:69], v[174:175]
	v_cvt_pk_bf16_f32 v180, v70, v71
	v_cvt_pk_bf16_f32 v181, v72, v73
	v_cvt_pk_bf16_f32 v182, v66, v67
	v_cvt_pk_bf16_f32 v183, v68, v69
	global_store_dwordx4 v[236:237], v[180:183], off offset:256 nt
	v_mad_i64_i32 v[234:235], s[4:5], v155, s33, v[232:233]
	v_pk_mul_f32 v[62:63], v[62:63], v[148:149] op_sel_hi:[1,0]
	v_pk_mul_f32 v[64:65], v[64:65], v[148:149] op_sel_hi:[1,0]
	v_pk_mul_f32 v[58:59], v[58:59], v[148:149] op_sel_hi:[1,0]
	v_pk_mul_f32 v[60:61], v[60:61], v[148:149] op_sel_hi:[1,0]
	v_pk_mul_f32 v[168:169], v[62:63], s[98:99] op_sel_hi:[1,0]
	v_pk_mul_f32 v[170:171], v[64:65], s[98:99] op_sel_hi:[1,0]
	v_pk_mul_f32 v[172:173], v[58:59], s[98:99] op_sel_hi:[1,0]
	v_pk_mul_f32 v[174:175], v[60:61], s[98:99] op_sel_hi:[1,0]
	v_exp_f32_e32 v168, v168
	v_exp_f32_e32 v169, v169
	v_exp_f32_e32 v170, v170
	v_exp_f32_e32 v171, v171
	v_exp_f32_e32 v172, v172
	v_exp_f32_e32 v173, v173
	v_exp_f32_e32 v174, v174
	v_exp_f32_e32 v175, v175
	v_pk_add_f32 v[168:169], v[168:169], 1.0 op_sel_hi:[1,0]
	v_pk_add_f32 v[170:171], v[170:171], 1.0 op_sel_hi:[1,0]
	v_pk_add_f32 v[172:173], v[172:173], 1.0 op_sel_hi:[1,0]
	v_pk_add_f32 v[174:175], v[174:175], 1.0 op_sel_hi:[1,0]
	v_rcp_f32_e32 v168, v168
	v_rcp_f32_e32 v169, v169
	v_rcp_f32_e32 v170, v170
	v_rcp_f32_e32 v171, v171
	v_rcp_f32_e32 v172, v172
	v_rcp_f32_e32 v173, v173
	v_rcp_f32_e32 v174, v174
	v_rcp_f32_e32 v175, v175
	v_pk_mul_f32 v[62:63], v[62:63], v[168:169]
	v_pk_mul_f32 v[64:65], v[64:65], v[170:171]
	v_pk_mul_f32 v[58:59], v[58:59], v[172:173]
	v_pk_mul_f32 v[60:61], v[60:61], v[174:175]
	v_cvt_pk_bf16_f32 v176, v62, v63
	v_cvt_pk_bf16_f32 v177, v64, v65
	v_cvt_pk_bf16_f32 v178, v58, v59
	v_cvt_pk_bf16_f32 v179, v60, v61
	global_store_dwordx4 v[234:235], v[176:179], off nt
	v_pk_mul_f32 v[50:51], v[50:51], v[148:149] op_sel_hi:[1,0]
	v_pk_mul_f32 v[52:53], v[52:53], v[148:149] op_sel_hi:[1,0]
	v_pk_mul_f32 v[42:43], v[42:43], v[148:149] op_sel_hi:[1,0]
	v_pk_mul_f32 v[44:45], v[44:45], v[148:149] op_sel_hi:[1,0]
	v_pk_mul_f32 v[168:169], v[50:51], s[98:99] op_sel_hi:[1,0]
	v_pk_mul_f32 v[170:171], v[52:53], s[98:99] op_sel_hi:[1,0]
	v_pk_mul_f32 v[172:173], v[42:43], s[98:99] op_sel_hi:[1,0]
	v_pk_mul_f32 v[174:175], v[44:45], s[98:99] op_sel_hi:[1,0]
	v_exp_f32_e32 v168, v168
	v_exp_f32_e32 v169, v169
	v_exp_f32_e32 v170, v170
	v_exp_f32_e32 v171, v171
	v_exp_f32_e32 v172, v172
	v_exp_f32_e32 v173, v173
	v_exp_f32_e32 v174, v174
	v_exp_f32_e32 v175, v175
	v_pk_add_f32 v[168:169], v[168:169], 1.0 op_sel_hi:[1,0]
	v_pk_add_f32 v[170:171], v[170:171], 1.0 op_sel_hi:[1,0]
	v_pk_add_f32 v[172:173], v[172:173], 1.0 op_sel_hi:[1,0]
	v_pk_add_f32 v[174:175], v[174:175], 1.0 op_sel_hi:[1,0]
	v_rcp_f32_e32 v168, v168
	v_rcp_f32_e32 v169, v169
	v_rcp_f32_e32 v170, v170
	v_rcp_f32_e32 v171, v171
	v_rcp_f32_e32 v172, v172
	v_rcp_f32_e32 v173, v173
	v_rcp_f32_e32 v174, v174
	v_rcp_f32_e32 v175, v175
	v_pk_mul_f32 v[50:51], v[50:51], v[168:169]
	v_pk_mul_f32 v[52:53], v[52:53], v[170:171]
	v_pk_mul_f32 v[42:43], v[42:43], v[172:173]
	v_pk_mul_f32 v[44:45], v[44:45], v[174:175]
	v_cvt_pk_bf16_f32 v180, v50, v51
	v_cvt_pk_bf16_f32 v181, v52, v53
	v_cvt_pk_bf16_f32 v182, v42, v43
	v_cvt_pk_bf16_f32 v183, v44, v45
	global_store_dwordx4 v[234:235], v[180:183], off offset:256 nt
	v_mad_i64_i32 v[236:237], s[4:5], v153, s33, v[232:233]
	v_pk_mul_f32 v[54:55], v[54:55], v[146:147] op_sel_hi:[1,0]
	v_pk_mul_f32 v[56:57], v[56:57], v[146:147] op_sel_hi:[1,0]
	v_pk_mul_f32 v[46:47], v[46:47], v[146:147] op_sel_hi:[1,0]
	v_pk_mul_f32 v[48:49], v[48:49], v[146:147] op_sel_hi:[1,0]
	v_pk_mul_f32 v[168:169], v[54:55], s[98:99] op_sel_hi:[1,0]
	v_pk_mul_f32 v[170:171], v[56:57], s[98:99] op_sel_hi:[1,0]
	v_pk_mul_f32 v[172:173], v[46:47], s[98:99] op_sel_hi:[1,0]
	v_pk_mul_f32 v[174:175], v[48:49], s[98:99] op_sel_hi:[1,0]
	v_exp_f32_e32 v168, v168
	v_exp_f32_e32 v169, v169
	v_exp_f32_e32 v170, v170
	v_exp_f32_e32 v171, v171
	v_exp_f32_e32 v172, v172
	v_exp_f32_e32 v173, v173
	v_exp_f32_e32 v174, v174
	v_exp_f32_e32 v175, v175
	v_pk_add_f32 v[168:169], v[168:169], 1.0 op_sel_hi:[1,0]
	v_pk_add_f32 v[170:171], v[170:171], 1.0 op_sel_hi:[1,0]
	v_pk_add_f32 v[172:173], v[172:173], 1.0 op_sel_hi:[1,0]
	v_pk_add_f32 v[174:175], v[174:175], 1.0 op_sel_hi:[1,0]
	v_rcp_f32_e32 v168, v168
	v_rcp_f32_e32 v169, v169
; __device__ __forceinline__ u32x4 pack8(f32x4 a, f32x4 b) { u32x4 w; w.x = cvt_pk_bf16(a[0], a[1]); w.y = cvt_pk_bf16(a[2], a[3]); w.z = cvt_pk_bf16(b[0], b[1]); w.w = cvt_pk_bf16(b[2], b[3]); return w; }
; __device__ __forceinline__ float sigmoid_f(float x) { return __builtin_amdgcn_rcpf(1.0f + __builtin_amdgcn_exp2f(-1.4426950409f * x)); }
; __device__ __forceinline__ float silu_f(float x) { return x * sigmoid_f(x); }
;     template <int ACT> __device__ __forceinline__ void body(f32x4 (&acc)[2][2][4][2], const Unit& u, int wr, int wc, int fr, int fq, int obase, const float (&rsv)[2][4]) const {
;     ...
;             for (int bj = 0; bj < 2; ++bj) { const int col = obase + bj * 128 + wc * 32 + 8 * fq;
;                 f32x4 v0 = acc[ai][bj][m][0] * rs, v1 = acc[ai][bj][m][1] * rs;
;                 if (ACT == 1) {
; #pragma unroll
;                     for (int j = 0; j < 4; ++j) { v0[j] = silu_f(v0[j]); v1[j] = silu_f(v1[j]); } }
;                 if (ACT == 2) {
; #pragma unroll
;                     for (int j = 0; j < 4; ++j) { v0[j] = sigmoid_f(v0[j]); v1[j] = sigmoid_f(v1[j]); } }
;                 __builtin_nontemporal_store(pack8(v0, v1), (u32x4*)(P + (size_t)row * NCO + col));
;             }
	v_rcp_f32_e32 v170, v170
	v_rcp_f32_e32 v171, v171
	v_rcp_f32_e32 v172, v172
	v_rcp_f32_e32 v173, v173
	v_rcp_f32_e32 v174, v174
	v_rcp_f32_e32 v175, v175
	v_pk_mul_f32 v[54:55], v[54:55], v[168:169]
	v_pk_mul_f32 v[56:57], v[56:57], v[170:171]
	v_pk_mul_f32 v[46:47], v[46:47], v[172:173]
	v_pk_mul_f32 v[48:49], v[48:49], v[174:175]
	v_cvt_pk_bf16_f32 v176, v54, v55
	v_cvt_pk_bf16_f32 v177, v56, v57
	v_cvt_pk_bf16_f32 v178, v46, v47
	v_cvt_pk_bf16_f32 v179, v48, v49
	global_store_dwordx4 v[236:237], v[176:179], off nt
	v_pk_mul_f32 v[34:35], v[34:35], v[146:147] op_sel_hi:[1,0]
	v_pk_mul_f32 v[36:37], v[36:37], v[146:147] op_sel_hi:[1,0]
	v_pk_mul_f32 v[26:27], v[26:27], v[146:147] op_sel_hi:[1,0]
	v_pk_mul_f32 v[28:29], v[28:29], v[146:147] op_sel_hi:[1,0]
	v_pk_mul_f32 v[168:169], v[34:35], s[98:99] op_sel_hi:[1,0]
	v_pk_mul_f32 v[170:171], v[36:37], s[98:99] op_sel_hi:[1,0]
	v_pk_mul_f32 v[172:173], v[26:27], s[98:99] op_sel_hi:[1,0]
	v_pk_mul_f32 v[174:175], v[28:29], s[98:99] op_sel_hi:[1,0]
	v_exp_f32_e32 v168, v168
	v_exp_f32_e32 v169, v169
	v_exp_f32_e32 v170, v170
	v_exp_f32_e32 v171, v171
	v_exp_f32_e32 v172, v172
	v_exp_f32_e32 v173, v173
	v_exp_f32_e32 v174, v174
	v_exp_f32_e32 v175, v175
	v_pk_add_f32 v[168:169], v[168:169], 1.0 op_sel_hi:[1,0]
	v_pk_add_f32 v[170:171], v[170:171], 1.0 op_sel_hi:[1,0]
	v_pk_add_f32 v[172:173], v[172:173], 1.0 op_sel_hi:[1,0]
	v_pk_add_f32 v[174:175], v[174:175], 1.0 op_sel_hi:[1,0]
	v_rcp_f32_e32 v168, v168
	v_rcp_f32_e32 v169, v169
	v_rcp_f32_e32 v170, v170
	v_rcp_f32_e32 v171, v171
	v_rcp_f32_e32 v172, v172
	v_rcp_f32_e32 v173, v173
	v_rcp_f32_e32 v174, v174
	v_rcp_f32_e32 v175, v175
	v_pk_mul_f32 v[34:35], v[34:35], v[168:169]
	v_pk_mul_f32 v[36:37], v[36:37], v[170:171]
	v_pk_mul_f32 v[26:27], v[26:27], v[172:173]
	v_pk_mul_f32 v[28:29], v[28:29], v[174:175]
	v_cvt_pk_bf16_f32 v180, v34, v35
	v_cvt_pk_bf16_f32 v181, v36, v37
	v_cvt_pk_bf16_f32 v182, v26, v27
	v_cvt_pk_bf16_f32 v183, v28, v29
	global_store_dwordx4 v[236:237], v[180:183], off offset:256 nt
	v_mad_i64_i32 v[234:235], s[4:5], v151, s33, v[232:233]
	v_pk_mul_f32 v[38:39], v[38:39], v[144:145] op_sel_hi:[1,0]
	v_pk_mul_f32 v[40:41], v[40:41], v[144:145] op_sel_hi:[1,0]
	v_pk_mul_f32 v[30:31], v[30:31], v[144:145] op_sel_hi:[1,0]
	v_pk_mul_f32 v[32:33], v[32:33], v[144:145] op_sel_hi:[1,0]
	v_pk_mul_f32 v[168:169], v[38:39], s[98:99] op_sel_hi:[1,0]
	v_pk_mul_f32 v[170:171], v[40:41], s[98:99] op_sel_hi:[1,0]
	v_pk_mul_f32 v[172:173], v[30:31], s[98:99] op_sel_hi:[1,0]
	v_pk_mul_f32 v[174:175], v[32:33], s[98:99] op_sel_hi:[1,0]
	v_exp_f32_e32 v168, v168
	v_exp_f32_e32 v169, v169
	v_exp_f32_e32 v170, v170
	v_exp_f32_e32 v171, v171
	v_exp_f32_e32 v172, v172
	v_exp_f32_e32 v173, v173
	v_exp_f32_e32 v174, v174
	v_exp_f32_e32 v175, v175
	v_pk_add_f32 v[168:169], v[168:169], 1.0 op_sel_hi:[1,0]
	v_pk_add_f32 v[170:171], v[170:171], 1.0 op_sel_hi:[1,0]
	v_pk_add_f32 v[172:173], v[172:173], 1.0 op_sel_hi:[1,0]
	v_pk_add_f32 v[174:175], v[174:175], 1.0 op_sel_hi:[1,0]
	v_rcp_f32_e32 v168, v168
	v_rcp_f32_e32 v169, v169
	v_rcp_f32_e32 v170, v170
	v_rcp_f32_e32 v171, v171
	v_rcp_f32_e32 v172, v172
	v_rcp_f32_e32 v173, v173
	v_rcp_f32_e32 v174, v174
	v_rcp_f32_e32 v175, v175
	v_pk_mul_f32 v[38:39], v[38:39], v[168:169]
	v_pk_mul_f32 v[40:41], v[40:41], v[170:171]
	v_pk_mul_f32 v[30:31], v[30:31], v[172:173]
	v_pk_mul_f32 v[32:33], v[32:33], v[174:175]
	v_cvt_pk_bf16_f32 v176, v38, v39
	v_cvt_pk_bf16_f32 v177, v40, v41
	v_cvt_pk_bf16_f32 v178, v30, v31
	v_cvt_pk_bf16_f32 v179, v32, v33
	global_store_dwordx4 v[234:235], v[176:179], off nt
	v_pk_mul_f32 v[18:19], v[18:19], v[144:145] op_sel_hi:[1,0]
	v_pk_mul_f32 v[20:21], v[20:21], v[144:145] op_sel_hi:[1,0]
	v_pk_mul_f32 v[10:11], v[10:11], v[144:145] op_sel_hi:[1,0]
	v_pk_mul_f32 v[12:13], v[12:13], v[144:145] op_sel_hi:[1,0]
	v_pk_mul_f32 v[168:169], v[18:19], s[98:99] op_sel_hi:[1,0]
	v_pk_mul_f32 v[170:171], v[20:21], s[98:99] op_sel_hi:[1,0]
	v_pk_mul_f32 v[172:173], v[10:11], s[98:99] op_sel_hi:[1,0]
	v_pk_mul_f32 v[174:175], v[12:13], s[98:99] op_sel_hi:[1,0]
; __device__ __forceinline__ float sigmoid_f(float x) { return __builtin_amdgcn_rcpf(1.0f + __builtin_amdgcn_exp2f(-1.4426950409f * x)); }
; __device__ __forceinline__ float silu_f(float x) { return x * sigmoid_f(x); }
; __device__ __forceinline__ u32x4 pack8(f32x4 a, f32x4 b) { u32x4 w; w.x = cvt_pk_bf16(a[0], a[1]); w.y = cvt_pk_bf16(a[2], a[3]); w.z = cvt_pk_bf16(b[0], b[1]); w.w = cvt_pk_bf16(b[2], b[3]); return w; }
;     template <int ACT> __device__ __forceinline__ void body(f32x4 (&acc)[2][2][4][2], const Unit& u, int wr, int wc, int fr, int fq, int obase, const float (&rsv)[2][4]) const {
;     ...
;             for (int bj = 0; bj < 2; ++bj) { const int col = obase + bj * 128 + wc * 32 + 8 * fq;
;                 f32x4 v0 = acc[ai][bj][m][0] * rs, v1 = acc[ai][bj][m][1] * rs;
;                 if (ACT == 1) {
; #pragma unroll
;                     for (int j = 0; j < 4; ++j) { v0[j] = silu_f(v0[j]); v1[j] = silu_f(v1[j]); } }
;                 if (ACT == 2) {
; #pragma unroll
;                     for (int j = 0; j < 4; ++j) { v0[j] = sigmoid_f(v0[j]); v1[j] = sigmoid_f(v1[j]); } }
;                 __builtin_nontemporal_store(pack8(v0, v1), (u32x4*)(P + (size_t)row * NCO + col));
;             }
	v_exp_f32_e32 v168, v168
	v_exp_f32_e32 v169, v169
	v_exp_f32_e32 v170, v170
	v_exp_f32_e32 v171, v171
	v_exp_f32_e32 v172, v172
	v_exp_f32_e32 v173, v173
	v_exp_f32_e32 v174, v174
	v_exp_f32_e32 v175, v175
	v_pk_add_f32 v[168:169], v[168:169], 1.0 op_sel_hi:[1,0]
	v_pk_add_f32 v[170:171], v[170:171], 1.0 op_sel_hi:[1,0]
	v_pk_add_f32 v[172:173], v[172:173], 1.0 op_sel_hi:[1,0]
	v_pk_add_f32 v[174:175], v[174:175], 1.0 op_sel_hi:[1,0]
	v_rcp_f32_e32 v168, v168
	v_rcp_f32_e32 v169, v169
	v_rcp_f32_e32 v170, v170
	v_rcp_f32_e32 v171, v171
	v_rcp_f32_e32 v172, v172
	v_rcp_f32_e32 v173, v173
	v_rcp_f32_e32 v174, v174
	v_rcp_f32_e32 v175, v175
	v_pk_mul_f32 v[18:19], v[18:19], v[168:169]
	v_pk_mul_f32 v[20:21], v[20:21], v[170:171]
	v_pk_mul_f32 v[10:11], v[10:11], v[172:173]
	v_pk_mul_f32 v[12:13], v[12:13], v[174:175]
	v_cvt_pk_bf16_f32 v180, v18, v19
	v_cvt_pk_bf16_f32 v181, v20, v21
	v_cvt_pk_bf16_f32 v182, v10, v11
	v_cvt_pk_bf16_f32 v183, v12, v13
	global_store_dwordx4 v[234:235], v[180:183], off offset:256 nt
	v_mad_i64_i32 v[236:237], s[4:5], v149, s33, v[232:233]
	v_pk_mul_f32 v[22:23], v[22:23], v[142:143] op_sel_hi:[1,0]
	v_pk_mul_f32 v[24:25], v[24:25], v[142:143] op_sel_hi:[1,0]
	v_pk_mul_f32 v[14:15], v[14:15], v[142:143] op_sel_hi:[1,0]
	v_pk_mul_f32 v[16:17], v[16:17], v[142:143] op_sel_hi:[1,0]
	v_pk_mul_f32 v[168:169], v[22:23], s[98:99] op_sel_hi:[1,0]
	v_pk_mul_f32 v[170:171], v[24:25], s[98:99] op_sel_hi:[1,0]
	v_pk_mul_f32 v[172:173], v[14:15], s[98:99] op_sel_hi:[1,0]
	v_pk_mul_f32 v[174:175], v[16:17], s[98:99] op_sel_hi:[1,0]
	v_exp_f32_e32 v168, v168
	v_exp_f32_e32 v169, v169
	v_exp_f32_e32 v170, v170
	v_exp_f32_e32 v171, v171
	v_exp_f32_e32 v172, v172
	v_exp_f32_e32 v173, v173
	v_exp_f32_e32 v174, v174
	v_exp_f32_e32 v175, v175
	v_pk_add_f32 v[168:169], v[168:169], 1.0 op_sel_hi:[1,0]
	v_pk_add_f32 v[170:171], v[170:171], 1.0 op_sel_hi:[1,0]
	v_pk_add_f32 v[172:173], v[172:173], 1.0 op_sel_hi:[1,0]
	v_pk_add_f32 v[174:175], v[174:175], 1.0 op_sel_hi:[1,0]
	v_rcp_f32_e32 v168, v168
	v_rcp_f32_e32 v169, v169
	v_rcp_f32_e32 v170, v170
	v_rcp_f32_e32 v171, v171
	v_rcp_f32_e32 v172, v172
	v_rcp_f32_e32 v173, v173
	v_rcp_f32_e32 v174, v174
	v_rcp_f32_e32 v175, v175
	v_pk_mul_f32 v[22:23], v[22:23], v[168:169]
	v_pk_mul_f32 v[24:25], v[24:25], v[170:171]
	v_pk_mul_f32 v[14:15], v[14:15], v[172:173]
	v_pk_mul_f32 v[16:17], v[16:17], v[174:175]
	v_cvt_pk_bf16_f32 v176, v22, v23
	v_cvt_pk_bf16_f32 v177, v24, v25
	v_cvt_pk_bf16_f32 v178, v14, v15
	v_cvt_pk_bf16_f32 v179, v16, v17
	global_store_dwordx4 v[236:237], v[176:179], off nt
	v_pk_mul_f32 v[6:7], v[6:7], v[142:143] op_sel_hi:[1,0]
	v_pk_mul_f32 v[8:9], v[8:9], v[142:143] op_sel_hi:[1,0]
	v_pk_mul_f32 v[2:3], v[2:3], v[142:143] op_sel_hi:[1,0]
	v_pk_mul_f32 v[4:5], v[4:5], v[142:143] op_sel_hi:[1,0]
	v_pk_mul_f32 v[168:169], v[6:7], s[98:99] op_sel_hi:[1,0]
	v_pk_mul_f32 v[170:171], v[8:9], s[98:99] op_sel_hi:[1,0]
	v_pk_mul_f32 v[172:173], v[2:3], s[98:99] op_sel_hi:[1,0]
	v_pk_mul_f32 v[174:175], v[4:5], s[98:99] op_sel_hi:[1,0]
	v_exp_f32_e32 v168, v168
	v_exp_f32_e32 v169, v169
	v_exp_f32_e32 v170, v170
	v_exp_f32_e32 v171, v171
	v_exp_f32_e32 v172, v172
	v_exp_f32_e32 v173, v173
	v_exp_f32_e32 v174, v174
	v_exp_f32_e32 v175, v175
	v_pk_add_f32 v[168:169], v[168:169], 1.0 op_sel_hi:[1,0]
	v_pk_add_f32 v[170:171], v[170:171], 1.0 op_sel_hi:[1,0]
	v_pk_add_f32 v[172:173], v[172:173], 1.0 op_sel_hi:[1,0]
	v_pk_add_f32 v[174:175], v[174:175], 1.0 op_sel_hi:[1,0]
	v_rcp_f32_e32 v168, v168
	v_rcp_f32_e32 v169, v169
	v_rcp_f32_e32 v170, v170
	v_rcp_f32_e32 v171, v171
	v_rcp_f32_e32 v172, v172
	v_rcp_f32_e32 v173, v173
	v_rcp_f32_e32 v174, v174
	v_rcp_f32_e32 v175, v175
	v_pk_mul_f32 v[6:7], v[6:7], v[168:169]
	v_pk_mul_f32 v[8:9], v[8:9], v[170:171]
	v_pk_mul_f32 v[2:3], v[2:3], v[172:173]
	v_pk_mul_f32 v[4:5], v[4:5], v[174:175]
	v_cvt_pk_bf16_f32 v180, v6, v7
	v_cvt_pk_bf16_f32 v181, v8, v9
	v_cvt_pk_bf16_f32 v182, v2, v3
	v_cvt_pk_bf16_f32 v183, v4, v5
	global_store_dwordx4 v[236:237], v[180:183], off offset:256 nt

; __device__ __forceinline__ float sigmoid_f(float x) { return __builtin_amdgcn_rcpf(1.0f + __builtin_amdgcn_exp2f(-1.4426950409f * x)); }
; __device__ __forceinline__ float silu_f(float x) { return x * sigmoid_f(x); }
; __device__ __forceinline__ u32x4 pack8(f32x4 a, f32x4 b) { u32x4 w; w.x = cvt_pk_bf16(a[0], a[1]); w.y = cvt_pk_bf16(a[2], a[3]); w.z = cvt_pk_bf16(b[0], b[1]); w.w = cvt_pk_bf16(b[2], b[3]); return w; }
;     template <int ACT> __device__ __forceinline__ void body_pair(f32x4 (&acc)[2][2][4][2], const Unit& u, int wr, int wc, int fr, int fq, int obase, const float (&rsv)[2][4]) const {
;         EPI_ROWS_BEGIN
;             const float rs = rsv[ai][m]; const int col = obase + wc * 32 + 8 * fq;
;             f32x4 a0 = acc[ai][0][m][0] * rs, a1 = acc[ai][0][m][1] * rs, b0 = acc[ai][1][m][0] * rs, b1 = acc[ai][1][m][1] * rs;
;             if (ACT == 1) {
; #pragma unroll
;                 for (int j = 0; j < 4; ++j) { b0[j] = silu_f(b0[j]); b1[j] = silu_f(b1[j]); } }
;             if (ACT == 2) {
; #pragma unroll
;                 for (int j = 0; j < 4; ++j) { b0[j] = sigmoid_f(b0[j]); b1[j] = sigmoid_f(b1[j]); } }
;             __builtin_nontemporal_store(pack8(a0 * b0, a1 * b1), (u32x4*)(P + (size_t)row * NCO + col));
;         EPI_END
.LBB0_209:
	s_andn2_b64 vcc, exec, s[4:5]
	s_cbranch_vccnz .LBB0_211
	s_lshl_b32 s4, s52, 7
	s_add_i32 s4, s29, s4
	s_mov_b32 s98, 0xbfb8aa3b
	v_lshl_add_u32 v228, v143, 3, s4
	v_lshlrev_b32_e32 v228, 1, v228
	v_ashrrev_i32_e32 v229, 31, v228
	v_lshl_add_u64 v[232:233], s[68:69], 0, v[228:229]
	v_mad_i64_i32 v[234:235], s[4:5], v154, s33, v[232:233]
	v_pk_mul_f32 v[118:119], v[118:119], v[158:159] op_sel_hi:[1,0]
	v_pk_mul_f32 v[120:121], v[120:121], v[158:159] op_sel_hi:[1,0]
	v_pk_mul_f32 v[110:111], v[110:111], v[158:159] op_sel_hi:[1,0]
	v_pk_mul_f32 v[112:113], v[112:113], v[158:159] op_sel_hi:[1,0]
	v_pk_mul_f32 v[168:169], v[118:119], s[98:99] op_sel_hi:[1,0]
	v_pk_mul_f32 v[170:171], v[120:121], s[98:99] op_sel_hi:[1,0]
	v_pk_mul_f32 v[172:173], v[110:111], s[98:99] op_sel_hi:[1,0]
	v_pk_mul_f32 v[174:175], v[112:113], s[98:99] op_sel_hi:[1,0]
	v_exp_f32_e32 v168, v168
	v_exp_f32_e32 v169, v169
	v_exp_f32_e32 v170, v170
	v_exp_f32_e32 v171, v171
	v_exp_f32_e32 v172, v172
	v_exp_f32_e32 v173, v173
	v_exp_f32_e32 v174, v174
	v_exp_f32_e32 v175, v175
	v_pk_mul_f32 v[126:127], v[126:127], v[158:159] op_sel_hi:[1,0]
	v_pk_mul_f32 v[128:129], v[128:129], v[158:159] op_sel_hi:[1,0]
	v_pk_mul_f32 v[122:123], v[122:123], v[158:159] op_sel_hi:[1,0]
	v_pk_mul_f32 v[124:125], v[124:125], v[158:159] op_sel_hi:[1,0]
	v_pk_add_f32 v[168:169], v[168:169], 1.0 op_sel_hi:[1,0]
	v_pk_add_f32 v[170:171], v[170:171], 1.0 op_sel_hi:[1,0]
	v_pk_add_f32 v[172:173], v[172:173], 1.0 op_sel_hi:[1,0]
	v_pk_add_f32 v[174:175], v[174:175], 1.0 op_sel_hi:[1,0]
	v_rcp_f32_e32 v168, v168
	v_rcp_f32_e32 v169, v169
	v_rcp_f32_e32 v170, v170
	v_rcp_f32_e32 v171, v171
	v_rcp_f32_e32 v172, v172
	v_rcp_f32_e32 v173, v173
	v_rcp_f32_e32 v174, v174
	v_rcp_f32_e32 v175, v175
	s_nop 0
	v_pk_mul_f32 v[126:127], v[126:127], v[168:169]
	v_pk_mul_f32 v[128:129], v[128:129], v[170:171]
	v_pk_mul_f32 v[122:123], v[122:123], v[172:173]
	v_pk_mul_f32 v[124:125], v[124:125], v[174:175]
	v_cvt_pk_bf16_f32 v176, v126, v127
	v_cvt_pk_bf16_f32 v177, v128, v129
	v_cvt_pk_bf16_f32 v178, v122, v123
	v_cvt_pk_bf16_f32 v179, v124, v125
	global_store_dwordx4 v[234:235], v[176:179], off nt
	v_mad_i64_i32 v[236:237], s[4:5], v209, s33, v[232:233]
	v_pk_mul_f32 v[98:99], v[98:99], v[156:157] op_sel_hi:[1,0]
	v_pk_mul_f32 v[100:101], v[100:101], v[156:157] op_sel_hi:[1,0]
	v_pk_mul_f32 v[90:91], v[90:91], v[156:157] op_sel_hi:[1,0]
	v_pk_mul_f32 v[92:93], v[92:93], v[156:157] op_sel_hi:[1,0]
	v_pk_mul_f32 v[168:169], v[98:99], s[98:99] op_sel_hi:[1,0]
	v_pk_mul_f32 v[170:171], v[100:101], s[98:99] op_sel_hi:[1,0]
	v_pk_mul_f32 v[172:173], v[90:91], s[98:99] op_sel_hi:[1,0]
	v_pk_mul_f32 v[174:175], v[92:93], s[98:99] op_sel_hi:[1,0]
	v_exp_f32_e32 v168, v168
	v_exp_f32_e32 v169, v169
	v_exp_f32_e32 v170, v170
	v_exp_f32_e32 v171, v171
	v_exp_f32_e32 v172, v172
	v_exp_f32_e32 v173, v173
	v_exp_f32_e32 v174, v174
	v_exp_f32_e32 v175, v175
	v_pk_mul_f32 v[114:115], v[114:115], v[156:157] op_sel_hi:[1,0]
	v_pk_mul_f32 v[116:117], v[116:117], v[156:157] op_sel_hi:[1,0]
	v_pk_mul_f32 v[106:107], v[106:107], v[156:157] op_sel_hi:[1,0]
	v_pk_mul_f32 v[108:109], v[108:109], v[156:157] op_sel_hi:[1,0]
	v_pk_add_f32 v[168:169], v[168:169], 1.0 op_sel_hi:[1,0]
	v_pk_add_f32 v[170:171], v[170:171], 1.0 op_sel_hi:[1,0]
	v_pk_add_f32 v[172:173], v[172:173], 1.0 op_sel_hi:[1,0]
	v_pk_add_f32 v[174:175], v[174:175], 1.0 op_sel_hi:[1,0]
	v_rcp_f32_e32 v168, v168
	v_rcp_f32_e32 v169, v169
	v_rcp_f32_e32 v170, v170
	v_rcp_f32_e32 v171, v171
	v_rcp_f32_e32 v172, v172
	v_rcp_f32_e32 v173, v173
	v_rcp_f32_e32 v174, v174
	v_rcp_f32_e32 v175, v175
	s_nop 0
	v_pk_mul_f32 v[114:115], v[114:115], v[168:169]
	v_pk_mul_f32 v[116:117], v[116:117], v[170:171]
	v_pk_mul_f32 v[106:107], v[106:107], v[172:173]
	v_pk_mul_f32 v[108:109], v[108:109], v[174:175]
	v_cvt_pk_bf16_f32 v180, v114, v115
	v_cvt_pk_bf16_f32 v181, v116, v117
	v_cvt_pk_bf16_f32 v182, v106, v107
	v_cvt_pk_bf16_f32 v183, v108, v109
	global_store_dwordx4 v[236:237], v[180:183], off nt
	v_mad_i64_i32 v[234:235], s[4:5], v208, s33, v[232:233]
	v_pk_mul_f32 v[82:83], v[82:83], v[152:153] op_sel_hi:[1,0]
	v_pk_mul_f32 v[84:85], v[84:85], v[152:153] op_sel_hi:[1,0]
	v_pk_mul_f32 v[74:75], v[74:75], v[152:153] op_sel_hi:[1,0]
	v_pk_mul_f32 v[76:77], v[76:77], v[152:153] op_sel_hi:[1,0]
	v_pk_mul_f32 v[168:169], v[82:83], s[98:99] op_sel_hi:[1,0]
	v_pk_mul_f32 v[170:171], v[84:85], s[98:99] op_sel_hi:[1,0]
	v_pk_mul_f32 v[172:173], v[74:75], s[98:99] op_sel_hi:[1,0]
	v_pk_mul_f32 v[174:175], v[76:77], s[98:99] op_sel_hi:[1,0]
	v_exp_f32_e32 v168, v168
	v_exp_f32_e32 v169, v169
	v_exp_f32_e32 v170, v170
	v_exp_f32_e32 v171, v171
	v_exp_f32_e32 v172, v172
	v_exp_f32_e32 v173, v173
	v_exp_f32_e32 v174, v174
	v_exp_f32_e32 v175, v175
	v_pk_mul_f32 v[102:103], v[102:103], v[152:153] op_sel_hi:[1,0]
	v_pk_mul_f32 v[104:105], v[104:105], v[152:153] op_sel_hi:[1,0]
	v_pk_mul_f32 v[94:95], v[94:95], v[152:153] op_sel_hi:[1,0]
	v_pk_mul_f32 v[96:97], v[96:97], v[152:153] op_sel_hi:[1,0]
	v_pk_add_f32 v[168:169], v[168:169], 1.0 op_sel_hi:[1,0]
	v_pk_add_f32 v[170:171], v[170:171], 1.0 op_sel_hi:[1,0]
	v_pk_add_f32 v[172:173], v[172:173], 1.0 op_sel_hi:[1,0]
	v_pk_add_f32 v[174:175], v[174:175], 1.0 op_sel_hi:[1,0]
	v_rcp_f32_e32 v168, v168
	v_rcp_f32_e32 v169, v169
	v_rcp_f32_e32 v170, v170
	v_rcp_f32_e32 v171, v171
	v_rcp_f32_e32 v172, v172
	v_rcp_f32_e32 v173, v173
	v_rcp_f32_e32 v174, v174
	v_rcp_f32_e32 v175, v175
	s_nop 0
	v_pk_mul_f32 v[102:103], v[102:103], v[168:169]
	v_pk_mul_f32 v[104:105], v[104:105], v[170:171]
	v_pk_mul_f32 v[94:95], v[94:95], v[172:173]
; __device__ __forceinline__ float sigmoid_f(float x) { return __builtin_amdgcn_rcpf(1.0f + __builtin_amdgcn_exp2f(-1.4426950409f * x)); }
; __device__ __forceinline__ float silu_f(float x) { return x * sigmoid_f(x); }
; __device__ __forceinline__ u32x4 pack8(f32x4 a, f32x4 b) { u32x4 w; w.x = cvt_pk_bf16(a[0], a[1]); w.y = cvt_pk_bf16(a[2], a[3]); w.z = cvt_pk_bf16(b[0], b[1]); w.w = cvt_pk_bf16(b[2], b[3]); return w; }
;     template <int ACT> __device__ __forceinline__ void body_pair(f32x4 (&acc)[2][2][4][2], const Unit& u, int wr, int wc, int fr, int fq, int obase, const float (&rsv)[2][4]) const {
;         EPI_ROWS_BEGIN
;             const float rs = rsv[ai][m]; const int col = obase + wc * 32 + 8 * fq;
;             f32x4 a0 = acc[ai][0][m][0] * rs, a1 = acc[ai][0][m][1] * rs, b0 = acc[ai][1][m][0] * rs, b1 = acc[ai][1][m][1] * rs;
;             if (ACT == 1) {
; #pragma unroll
;                 for (int j = 0; j < 4; ++j) { b0[j] = silu_f(b0[j]); b1[j] = silu_f(b1[j]); } }
;             if (ACT == 2) {
; #pragma unroll
;                 for (int j = 0; j < 4; ++j) { b0[j] = sigmoid_f(b0[j]); b1[j] = sigmoid_f(b1[j]); } }
;             __builtin_nontemporal_store(pack8(a0 * b0, a1 * b1), (u32x4*)(P + (size_t)row * NCO + col));
;         EPI_END
	v_pk_mul_f32 v[96:97], v[96:97], v[174:175]
	v_cvt_pk_bf16_f32 v176, v102, v103
	v_cvt_pk_bf16_f32 v177, v104, v105
	v_cvt_pk_bf16_f32 v178, v94, v95
	v_cvt_pk_bf16_f32 v179, v96, v97
	global_store_dwordx4 v[234:235], v[176:179], off nt
	v_mad_i64_i32 v[236:237], s[4:5], v157, s33, v[232:233]
	v_pk_mul_f32 v[70:71], v[70:71], v[150:151] op_sel_hi:[1,0]
	v_pk_mul_f32 v[72:73], v[72:73], v[150:151] op_sel_hi:[1,0]
	v_pk_mul_f32 v[66:67], v[66:67], v[150:151] op_sel_hi:[1,0]
	v_pk_mul_f32 v[68:69], v[68:69], v[150:151] op_sel_hi:[1,0]
	v_pk_mul_f32 v[168:169], v[70:71], s[98:99] op_sel_hi:[1,0]
	v_pk_mul_f32 v[170:171], v[72:73], s[98:99] op_sel_hi:[1,0]
	v_pk_mul_f32 v[172:173], v[66:67], s[98:99] op_sel_hi:[1,0]
	v_pk_mul_f32 v[174:175], v[68:69], s[98:99] op_sel_hi:[1,0]
	v_exp_f32_e32 v168, v168
	v_exp_f32_e32 v169, v169
	v_exp_f32_e32 v170, v170
	v_exp_f32_e32 v171, v171
	v_exp_f32_e32 v172, v172
	v_exp_f32_e32 v173, v173
	v_exp_f32_e32 v174, v174
	v_exp_f32_e32 v175, v175
	v_pk_mul_f32 v[86:87], v[86:87], v[150:151] op_sel_hi:[1,0]
	v_pk_mul_f32 v[88:89], v[88:89], v[150:151] op_sel_hi:[1,0]
	v_pk_mul_f32 v[78:79], v[78:79], v[150:151] op_sel_hi:[1,0]
	v_pk_mul_f32 v[80:81], v[80:81], v[150:151] op_sel_hi:[1,0]
	v_pk_add_f32 v[168:169], v[168:169], 1.0 op_sel_hi:[1,0]
	v_pk_add_f32 v[170:171], v[170:171], 1.0 op_sel_hi:[1,0]
	v_pk_add_f32 v[172:173], v[172:173], 1.0 op_sel_hi:[1,0]
	v_pk_add_f32 v[174:175], v[174:175], 1.0 op_sel_hi:[1,0]
	v_rcp_f32_e32 v168, v168
	v_rcp_f32_e32 v169, v169
	v_rcp_f32_e32 v170, v170
	v_rcp_f32_e32 v171, v171
	v_rcp_f32_e32 v172, v172
	v_rcp_f32_e32 v173, v173
	v_rcp_f32_e32 v174, v174
	v_rcp_f32_e32 v175, v175
	s_nop 0
	v_pk_mul_f32 v[86:87], v[86:87], v[168:169]
	v_pk_mul_f32 v[88:89], v[88:89], v[170:171]
	v_pk_mul_f32 v[78:79], v[78:79], v[172:173]
	v_pk_mul_f32 v[80:81], v[80:81], v[174:175]
	v_cvt_pk_bf16_f32 v180, v86, v87
	v_cvt_pk_bf16_f32 v181, v88, v89
	v_cvt_pk_bf16_f32 v182, v78, v79
	v_cvt_pk_bf16_f32 v183, v80, v81
	global_store_dwordx4 v[236:237], v[180:183], off nt
	v_mad_i64_i32 v[234:235], s[4:5], v155, s33, v[232:233]
	v_pk_mul_f32 v[50:51], v[50:51], v[148:149] op_sel_hi:[1,0]
	v_pk_mul_f32 v[52:53], v[52:53], v[148:149] op_sel_hi:[1,0]
	v_pk_mul_f32 v[42:43], v[42:43], v[148:149] op_sel_hi:[1,0]
	v_pk_mul_f32 v[44:45], v[44:45], v[148:149] op_sel_hi:[1,0]
	v_pk_mul_f32 v[168:169], v[50:51], s[98:99] op_sel_hi:[1,0]
	v_pk_mul_f32 v[170:171], v[52:53], s[98:99] op_sel_hi:[1,0]
	v_pk_mul_f32 v[172:173], v[42:43], s[98:99] op_sel_hi:[1,0]
	v_pk_mul_f32 v[174:175], v[44:45], s[98:99] op_sel_hi:[1,0]
	v_exp_f32_e32 v168, v168
	v_exp_f32_e32 v169, v169
	v_exp_f32_e32 v170, v170
	v_exp_f32_e32 v171, v171
	v_exp_f32_e32 v172, v172
	v_exp_f32_e32 v173, v173
	v_exp_f32_e32 v174, v174
	v_exp_f32_e32 v175, v175
	v_pk_mul_f32 v[62:63], v[62:63], v[148:149] op_sel_hi:[1,0]
	v_pk_mul_f32 v[64:65], v[64:65], v[148:149] op_sel_hi:[1,0]
	v_pk_mul_f32 v[58:59], v[58:59], v[148:149] op_sel_hi:[1,0]
	v_pk_mul_f32 v[60:61], v[60:61], v[148:149] op_sel_hi:[1,0]
	v_pk_add_f32 v[168:169], v[168:169], 1.0 op_sel_hi:[1,0]
	v_pk_add_f32 v[170:171], v[170:171], 1.0 op_sel_hi:[1,0]
	v_pk_add_f32 v[172:173], v[172:173], 1.0 op_sel_hi:[1,0]
	v_pk_add_f32 v[174:175], v[174:175], 1.0 op_sel_hi:[1,0]
	v_rcp_f32_e32 v168, v168
	v_rcp_f32_e32 v169, v169
	v_rcp_f32_e32 v170, v170
	v_rcp_f32_e32 v171, v171
	v_rcp_f32_e32 v172, v172
	v_rcp_f32_e32 v173, v173
	v_rcp_f32_e32 v174, v174
	v_rcp_f32_e32 v175, v175
	s_nop 0
	v_pk_mul_f32 v[62:63], v[62:63], v[168:169]
	v_pk_mul_f32 v[64:65], v[64:65], v[170:171]
	v_pk_mul_f32 v[58:59], v[58:59], v[172:173]
	v_pk_mul_f32 v[60:61], v[60:61], v[174:175]
	v_cvt_pk_bf16_f32 v176, v62, v63
	v_cvt_pk_bf16_f32 v177, v64, v65
	v_cvt_pk_bf16_f32 v178, v58, v59
	v_cvt_pk_bf16_f32 v179, v60, v61
	global_store_dwordx4 v[234:235], v[176:179], off nt
	v_mad_i64_i32 v[236:237], s[4:5], v153, s33, v[232:233]
	v_pk_mul_f32 v[34:35], v[34:35], v[146:147] op_sel_hi:[1,0]
	v_pk_mul_f32 v[36:37], v[36:37], v[146:147] op_sel_hi:[1,0]
	v_pk_mul_f32 v[26:27], v[26:27], v[146:147] op_sel_hi:[1,0]
	v_pk_mul_f32 v[28:29], v[28:29], v[146:147] op_sel_hi:[1,0]
	v_pk_mul_f32 v[168:169], v[34:35], s[98:99] op_sel_hi:[1,0]
	v_pk_mul_f32 v[170:171], v[36:37], s[98:99] op_sel_hi:[1,0]
	v_pk_mul_f32 v[172:173], v[26:27], s[98:99] op_sel_hi:[1,0]
	v_pk_mul_f32 v[174:175], v[28:29], s[98:99] op_sel_hi:[1,0]
	v_exp_f32_e32 v168, v168
	v_exp_f32_e32 v169, v169
	v_exp_f32_e32 v170, v170
	v_exp_f32_e32 v171, v171
	v_exp_f32_e32 v172, v172
	v_exp_f32_e32 v173, v173
	v_exp_f32_e32 v174, v174
	v_exp_f32_e32 v175, v175
; __device__ __forceinline__ float sigmoid_f(float x) { return __builtin_amdgcn_rcpf(1.0f + __builtin_amdgcn_exp2f(-1.4426950409f * x)); }
; __device__ __forceinline__ float silu_f(float x) { return x * sigmoid_f(x); }
; __device__ __forceinline__ u32x4 pack8(f32x4 a, f32x4 b) { u32x4 w; w.x = cvt_pk_bf16(a[0], a[1]); w.y = cvt_pk_bf16(a[2], a[3]); w.z = cvt_pk_bf16(b[0], b[1]); w.w = cvt_pk_bf16(b[2], b[3]); return w; }
;     template <int ACT> __device__ __forceinline__ void body_pair(f32x4 (&acc)[2][2][4][2], const Unit& u, int wr, int wc, int fr, int fq, int obase, const float (&rsv)[2][4]) const {
;         EPI_ROWS_BEGIN
;             const float rs = rsv[ai][m]; const int col = obase + wc * 32 + 8 * fq;
;             f32x4 a0 = acc[ai][0][m][0] * rs, a1 = acc[ai][0][m][1] * rs, b0 = acc[ai][1][m][0] * rs, b1 = acc[ai][1][m][1] * rs;
;             if (ACT == 1) {
; #pragma unroll
;                 for (int j = 0; j < 4; ++j) { b0[j] = silu_f(b0[j]); b1[j] = silu_f(b1[j]); } }
;             if (ACT == 2) {
; #pragma unroll
;                 for (int j = 0; j < 4; ++j) { b0[j] = sigmoid_f(b0[j]); b1[j] = sigmoid_f(b1[j]); } }
;             __builtin_nontemporal_store(pack8(a0 * b0, a1 * b1), (u32x4*)(P + (size_t)row * NCO + col));
;         EPI_END
	v_pk_mul_f32 v[54:55], v[54:55], v[146:147] op_sel_hi:[1,0]
	v_pk_mul_f32 v[56:57], v[56:57], v[146:147] op_sel_hi:[1,0]
	v_pk_mul_f32 v[46:47], v[46:47], v[146:147] op_sel_hi:[1,0]
	v_pk_mul_f32 v[48:49], v[48:49], v[146:147] op_sel_hi:[1,0]
	v_pk_add_f32 v[168:169], v[168:169], 1.0 op_sel_hi:[1,0]
	v_pk_add_f32 v[170:171], v[170:171], 1.0 op_sel_hi:[1,0]
	v_pk_add_f32 v[172:173], v[172:173], 1.0 op_sel_hi:[1,0]
	v_pk_add_f32 v[174:175], v[174:175], 1.0 op_sel_hi:[1,0]
	v_rcp_f32_e32 v168, v168
	v_rcp_f32_e32 v169, v169
	v_rcp_f32_e32 v170, v170
	v_rcp_f32_e32 v171, v171
	v_rcp_f32_e32 v172, v172
	v_rcp_f32_e32 v173, v173
	v_rcp_f32_e32 v174, v174
	v_rcp_f32_e32 v175, v175
	s_nop 0
	v_pk_mul_f32 v[54:55], v[54:55], v[168:169]
	v_pk_mul_f32 v[56:57], v[56:57], v[170:171]
	v_pk_mul_f32 v[46:47], v[46:47], v[172:173]
	v_pk_mul_f32 v[48:49], v[48:49], v[174:175]
	v_cvt_pk_bf16_f32 v180, v54, v55
	v_cvt_pk_bf16_f32 v181, v56, v57
	v_cvt_pk_bf16_f32 v182, v46, v47
	v_cvt_pk_bf16_f32 v183, v48, v49
	global_store_dwordx4 v[236:237], v[180:183], off nt
	v_mad_i64_i32 v[234:235], s[4:5], v151, s33, v[232:233]
	v_pk_mul_f32 v[18:19], v[18:19], v[144:145] op_sel_hi:[1,0]
	v_pk_mul_f32 v[20:21], v[20:21], v[144:145] op_sel_hi:[1,0]
	v_pk_mul_f32 v[10:11], v[10:11], v[144:145] op_sel_hi:[1,0]
	v_pk_mul_f32 v[12:13], v[12:13], v[144:145] op_sel_hi:[1,0]
	v_pk_mul_f32 v[168:169], v[18:19], s[98:99] op_sel_hi:[1,0]
	v_pk_mul_f32 v[170:171], v[20:21], s[98:99] op_sel_hi:[1,0]
	v_pk_mul_f32 v[172:173], v[10:11], s[98:99] op_sel_hi:[1,0]
	v_pk_mul_f32 v[174:175], v[12:13], s[98:99] op_sel_hi:[1,0]
	v_exp_f32_e32 v168, v168
	v_exp_f32_e32 v169, v169
	v_exp_f32_e32 v170, v170
	v_exp_f32_e32 v171, v171
	v_exp_f32_e32 v172, v172
	v_exp_f32_e32 v173, v173
	v_exp_f32_e32 v174, v174
	v_exp_f32_e32 v175, v175
	v_pk_mul_f32 v[38:39], v[38:39], v[144:145] op_sel_hi:[1,0]
	v_pk_mul_f32 v[40:41], v[40:41], v[144:145] op_sel_hi:[1,0]
	v_pk_mul_f32 v[30:31], v[30:31], v[144:145] op_sel_hi:[1,0]
	v_pk_mul_f32 v[32:33], v[32:33], v[144:145] op_sel_hi:[1,0]
	v_pk_add_f32 v[168:169], v[168:169], 1.0 op_sel_hi:[1,0]
	v_pk_add_f32 v[170:171], v[170:171], 1.0 op_sel_hi:[1,0]
	v_pk_add_f32 v[172:173], v[172:173], 1.0 op_sel_hi:[1,0]
	v_pk_add_f32 v[174:175], v[174:175], 1.0 op_sel_hi:[1,0]
	v_rcp_f32_e32 v168, v168
	v_rcp_f32_e32 v169, v169
	v_rcp_f32_e32 v170, v170
	v_rcp_f32_e32 v171, v171
	v_rcp_f32_e32 v172, v172
	v_rcp_f32_e32 v173, v173
	v_rcp_f32_e32 v174, v174
	v_rcp_f32_e32 v175, v175
	s_nop 0
	v_pk_mul_f32 v[38:39], v[38:39], v[168:169]
	v_pk_mul_f32 v[40:41], v[40:41], v[170:171]
	v_pk_mul_f32 v[30:31], v[30:31], v[172:173]
	v_pk_mul_f32 v[32:33], v[32:33], v[174:175]
	v_cvt_pk_bf16_f32 v176, v38, v39
	v_cvt_pk_bf16_f32 v177, v40, v41
	v_cvt_pk_bf16_f32 v178, v30, v31
	v_cvt_pk_bf16_f32 v179, v32, v33
	global_store_dwordx4 v[234:235], v[176:179], off nt
	v_mad_i64_i32 v[236:237], s[4:5], v149, s33, v[232:233]
	v_pk_mul_f32 v[6:7], v[6:7], v[142:143] op_sel_hi:[1,0]
	v_pk_mul_f32 v[8:9], v[8:9], v[142:143] op_sel_hi:[1,0]
	v_pk_mul_f32 v[2:3], v[2:3], v[142:143] op_sel_hi:[1,0]
	v_pk_mul_f32 v[4:5], v[4:5], v[142:143] op_sel_hi:[1,0]
	v_pk_mul_f32 v[168:169], v[6:7], s[98:99] op_sel_hi:[1,0]
	v_pk_mul_f32 v[170:171], v[8:9], s[98:99] op_sel_hi:[1,0]
	v_pk_mul_f32 v[172:173], v[2:3], s[98:99] op_sel_hi:[1,0]
	v_pk_mul_f32 v[174:175], v[4:5], s[98:99] op_sel_hi:[1,0]
	v_exp_f32_e32 v168, v168
	v_exp_f32_e32 v169, v169
	v_exp_f32_e32 v170, v170
	v_exp_f32_e32 v171, v171
	v_exp_f32_e32 v172, v172
	v_exp_f32_e32 v173, v173
	v_exp_f32_e32 v174, v174
	v_exp_f32_e32 v175, v175
	v_pk_mul_f32 v[22:23], v[22:23], v[142:143] op_sel_hi:[1,0]
	v_pk_mul_f32 v[24:25], v[24:25], v[142:143] op_sel_hi:[1,0]
	v_pk_mul_f32 v[14:15], v[14:15], v[142:143] op_sel_hi:[1,0]
	v_pk_mul_f32 v[16:17], v[16:17], v[142:143] op_sel_hi:[1,0]
	v_pk_add_f32 v[168:169], v[168:169], 1.0 op_sel_hi:[1,0]
	v_pk_add_f32 v[170:171], v[170:171], 1.0 op_sel_hi:[1,0]
	v_pk_add_f32 v[172:173], v[172:173], 1.0 op_sel_hi:[1,0]
	v_pk_add_f32 v[174:175], v[174:175], 1.0 op_sel_hi:[1,0]
	v_rcp_f32_e32 v168, v168
	v_rcp_f32_e32 v169, v169
	v_rcp_f32_e32 v170, v170
	v_rcp_f32_e32 v171, v171
	v_rcp_f32_e32 v172, v172
	v_rcp_f32_e32 v173, v173
	v_rcp_f32_e32 v174, v174
	v_rcp_f32_e32 v175, v175
	s_nop 0
	v_pk_mul_f32 v[22:23], v[22:23], v[168:169]
	v_pk_mul_f32 v[24:25], v[24:25], v[170:171]
	v_pk_mul_f32 v[14:15], v[14:15], v[172:173]
	v_pk_mul_f32 v[16:17], v[16:17], v[174:175]
	v_cvt_pk_bf16_f32 v180, v22, v23
	v_cvt_pk_bf16_f32 v181, v24, v25
	v_cvt_pk_bf16_f32 v182, v14, v15
	v_cvt_pk_bf16_f32 v183, v16, v17
	global_store_dwordx4 v[236:237], v[180:183], off nt

; __device__ __forceinline__ float sigmoid_f(float x) { return __builtin_amdgcn_rcpf(1.0f + __builtin_amdgcn_exp2f(-1.4426950409f * x)); }
; __device__ __forceinline__ float silu_f(float x) { return x * sigmoid_f(x); }
; __device__ __forceinline__ u32x4 pack8(f32x4 a, f32x4 b) { u32x4 w; w.x = cvt_pk_bf16(a[0], a[1]); w.y = cvt_pk_bf16(a[2], a[3]); w.z = cvt_pk_bf16(b[0], b[1]); w.w = cvt_pk_bf16(b[2], b[3]); return w; }
;     template <int ACT> __device__ __forceinline__ void body(f32x4 (&acc)[2][2][4][2], const Unit& u, int wr, int wc, int fr, int fq, int obase, const float (&rsv)[2][4]) const {
;     ...
;             for (int bj = 0; bj < 2; ++bj) { const int col = obase + bj * 128 + wc * 32 + 8 * fq;
;                 f32x4 v0 = acc[ai][bj][m][0] * rs, v1 = acc[ai][bj][m][1] * rs;
;                 if (ACT == 1) {
; #pragma unroll
;                     for (int j = 0; j < 4; ++j) { v0[j] = silu_f(v0[j]); v1[j] = silu_f(v1[j]); } }
;                 if (ACT == 2) {
; #pragma unroll
;                     for (int j = 0; j < 4; ++j) { v0[j] = sigmoid_f(v0[j]); v1[j] = sigmoid_f(v1[j]); } }
;                 __builtin_nontemporal_store(pack8(v0, v1), (u32x4*)(P + (size_t)row * NCO + col));
;             }
.LBB0_212:
	s_andn2_b64 vcc, exec, s[4:5]
	s_cbranch_vccnz .LBB0_214
	s_lshl_b32 s4, s52, 8
	s_add_i32 s4, s4, s16
	s_mov_b32 s98, 0xbfb8aa3b
	v_lshl_add_u32 v228, v143, 3, s4
	v_lshlrev_b32_e32 v228, 1, v228
	v_ashrrev_i32_e32 v229, 31, v228
	v_lshl_add_u64 v[232:233], s[68:69], 0, v[228:229]
	v_mad_i64_i32 v[234:235], s[4:5], v154, s33, v[232:233]
	v_pk_mul_f32 v[126:127], v[126:127], v[158:159] op_sel_hi:[1,0]
	v_pk_mul_f32 v[128:129], v[128:129], v[158:159] op_sel_hi:[1,0]
	v_pk_mul_f32 v[122:123], v[122:123], v[158:159] op_sel_hi:[1,0]
	v_pk_mul_f32 v[124:125], v[124:125], v[158:159] op_sel_hi:[1,0]
	v_pk_mul_f32 v[168:169], v[126:127], s[98:99] op_sel_hi:[1,0]
	v_pk_mul_f32 v[170:171], v[128:129], s[98:99] op_sel_hi:[1,0]
	v_pk_mul_f32 v[172:173], v[122:123], s[98:99] op_sel_hi:[1,0]
	v_pk_mul_f32 v[174:175], v[124:125], s[98:99] op_sel_hi:[1,0]
	v_exp_f32_e32 v168, v168
	v_exp_f32_e32 v169, v169
	v_exp_f32_e32 v170, v170
	v_exp_f32_e32 v171, v171
	v_exp_f32_e32 v172, v172
	v_exp_f32_e32 v173, v173
	v_exp_f32_e32 v174, v174
	v_exp_f32_e32 v175, v175
	v_pk_add_f32 v[168:169], v[168:169], 1.0 op_sel_hi:[1,0]
	v_pk_add_f32 v[170:171], v[170:171], 1.0 op_sel_hi:[1,0]
	v_pk_add_f32 v[172:173], v[172:173], 1.0 op_sel_hi:[1,0]
	v_pk_add_f32 v[174:175], v[174:175], 1.0 op_sel_hi:[1,0]
	v_rcp_f32_e32 v168, v168
	v_rcp_f32_e32 v169, v169
	v_rcp_f32_e32 v170, v170
	v_rcp_f32_e32 v171, v171
	v_rcp_f32_e32 v172, v172
	v_rcp_f32_e32 v173, v173
	v_rcp_f32_e32 v174, v174
	v_rcp_f32_e32 v175, v175
	v_pk_mul_f32 v[126:127], v[126:127], v[168:169]
	v_pk_mul_f32 v[128:129], v[128:129], v[170:171]
	v_pk_mul_f32 v[122:123], v[122:123], v[172:173]
	v_pk_mul_f32 v[124:125], v[124:125], v[174:175]
	v_cvt_pk_bf16_f32 v176, v126, v127
	v_cvt_pk_bf16_f32 v177, v128, v129
	v_cvt_pk_bf16_f32 v178, v122, v123
	v_cvt_pk_bf16_f32 v179, v124, v125
	global_store_dwordx4 v[234:235], v[176:179], off nt
	v_pk_mul_f32 v[118:119], v[118:119], v[158:159] op_sel_hi:[1,0]
	v_pk_mul_f32 v[120:121], v[120:121], v[158:159] op_sel_hi:[1,0]
	v_pk_mul_f32 v[110:111], v[110:111], v[158:159] op_sel_hi:[1,0]
	v_pk_mul_f32 v[112:113], v[112:113], v[158:159] op_sel_hi:[1,0]
	v_pk_mul_f32 v[168:169], v[118:119], s[98:99] op_sel_hi:[1,0]
	v_pk_mul_f32 v[170:171], v[120:121], s[98:99] op_sel_hi:[1,0]
	v_pk_mul_f32 v[172:173], v[110:111], s[98:99] op_sel_hi:[1,0]
	v_pk_mul_f32 v[174:175], v[112:113], s[98:99] op_sel_hi:[1,0]
	v_exp_f32_e32 v168, v168
	v_exp_f32_e32 v169, v169
	v_exp_f32_e32 v170, v170
	v_exp_f32_e32 v171, v171
	v_exp_f32_e32 v172, v172
	v_exp_f32_e32 v173, v173
	v_exp_f32_e32 v174, v174
	v_exp_f32_e32 v175, v175
	v_pk_add_f32 v[168:169], v[168:169], 1.0 op_sel_hi:[1,0]
	v_pk_add_f32 v[170:171], v[170:171], 1.0 op_sel_hi:[1,0]
	v_pk_add_f32 v[172:173], v[172:173], 1.0 op_sel_hi:[1,0]
	v_pk_add_f32 v[174:175], v[174:175], 1.0 op_sel_hi:[1,0]
	v_rcp_f32_e32 v168, v168
	v_rcp_f32_e32 v169, v169
	v_rcp_f32_e32 v170, v170
	v_rcp_f32_e32 v171, v171
	v_rcp_f32_e32 v172, v172
	v_rcp_f32_e32 v173, v173
	v_rcp_f32_e32 v174, v174
	v_rcp_f32_e32 v175, v175
	v_pk_mul_f32 v[118:119], v[118:119], v[168:169]
	v_pk_mul_f32 v[120:121], v[120:121], v[170:171]
	v_pk_mul_f32 v[110:111], v[110:111], v[172:173]
	v_pk_mul_f32 v[112:113], v[112:113], v[174:175]
	v_cvt_pk_bf16_f32 v180, v118, v119
	v_cvt_pk_bf16_f32 v181, v120, v121
	v_cvt_pk_bf16_f32 v182, v110, v111
	v_cvt_pk_bf16_f32 v183, v112, v113
	global_store_dwordx4 v[234:235], v[180:183], off offset:256 nt
	v_mad_i64_i32 v[236:237], s[4:5], v209, s33, v[232:233]
	v_pk_mul_f32 v[114:115], v[114:115], v[156:157] op_sel_hi:[1,0]
	v_pk_mul_f32 v[116:117], v[116:117], v[156:157] op_sel_hi:[1,0]
	v_pk_mul_f32 v[106:107], v[106:107], v[156:157] op_sel_hi:[1,0]
	v_pk_mul_f32 v[108:109], v[108:109], v[156:157] op_sel_hi:[1,0]
	v_pk_mul_f32 v[168:169], v[114:115], s[98:99] op_sel_hi:[1,0]
	v_pk_mul_f32 v[170:171], v[116:117], s[98:99] op_sel_hi:[1,0]
	v_pk_mul_f32 v[172:173], v[106:107], s[98:99] op_sel_hi:[1,0]
	v_pk_mul_f32 v[174:175], v[108:109], s[98:99] op_sel_hi:[1,0]
	v_exp_f32_e32 v168, v168
	v_exp_f32_e32 v169, v169
	v_exp_f32_e32 v170, v170
	v_exp_f32_e32 v171, v171
	v_exp_f32_e32 v172, v172
	v_exp_f32_e32 v173, v173
	v_exp_f32_e32 v174, v174
	v_exp_f32_e32 v175, v175
	v_pk_add_f32 v[168:169], v[168:169], 1.0 op_sel_hi:[1,0]
	v_pk_add_f32 v[170:171], v[170:171], 1.0 op_sel_hi:[1,0]
	v_pk_add_f32 v[172:173], v[172:173], 1.0 op_sel_hi:[1,0]
	v_pk_add_f32 v[174:175], v[174:175], 1.0 op_sel_hi:[1,0]
	v_rcp_f32_e32 v168, v168
	v_rcp_f32_e32 v169, v169
	v_rcp_f32_e32 v170, v170
	v_rcp_f32_e32 v171, v171
	v_rcp_f32_e32 v172, v172
	v_rcp_f32_e32 v173, v173
	v_rcp_f32_e32 v174, v174
	v_rcp_f32_e32 v175, v175
	v_pk_mul_f32 v[114:115], v[114:115], v[168:169]
	v_pk_mul_f32 v[116:117], v[116:117], v[170:171]
	v_pk_mul_f32 v[106:107], v[106:107], v[172:173]
	v_pk_mul_f32 v[108:109], v[108:109], v[174:175]
	v_cvt_pk_bf16_f32 v176, v114, v115
	v_cvt_pk_bf16_f32 v177, v116, v117
	v_cvt_pk_bf16_f32 v178, v106, v107
	v_cvt_pk_bf16_f32 v179, v108, v109
	global_store_dwordx4 v[236:237], v[176:179], off nt
	v_pk_mul_f32 v[98:99], v[98:99], v[156:157] op_sel_hi:[1,0]
	v_pk_mul_f32 v[100:101], v[100:101], v[156:157] op_sel_hi:[1,0]
	v_pk_mul_f32 v[90:91], v[90:91], v[156:157] op_sel_hi:[1,0]
	v_pk_mul_f32 v[92:93], v[92:93], v[156:157] op_sel_hi:[1,0]
	v_pk_mul_f32 v[168:169], v[98:99], s[98:99] op_sel_hi:[1,0]
	v_pk_mul_f32 v[170:171], v[100:101], s[98:99] op_sel_hi:[1,0]
	v_pk_mul_f32 v[172:173], v[90:91], s[98:99] op_sel_hi:[1,0]
	v_pk_mul_f32 v[174:175], v[92:93], s[98:99] op_sel_hi:[1,0]
	v_exp_f32_e32 v168, v168
	v_exp_f32_e32 v169, v169
	v_exp_f32_e32 v170, v170
; __device__ __forceinline__ float sigmoid_f(float x) { return __builtin_amdgcn_rcpf(1.0f + __builtin_amdgcn_exp2f(-1.4426950409f * x)); }
; __device__ __forceinline__ float silu_f(float x) { return x * sigmoid_f(x); }
; __device__ __forceinline__ u32x4 pack8(f32x4 a, f32x4 b) { u32x4 w; w.x = cvt_pk_bf16(a[0], a[1]); w.y = cvt_pk_bf16(a[2], a[3]); w.z = cvt_pk_bf16(b[0], b[1]); w.w = cvt_pk_bf16(b[2], b[3]); return w; }
;     template <int ACT> __device__ __forceinline__ void body(f32x4 (&acc)[2][2][4][2], const Unit& u, int wr, int wc, int fr, int fq, int obase, const float (&rsv)[2][4]) const {
;     ...
;             for (int bj = 0; bj < 2; ++bj) { const int col = obase + bj * 128 + wc * 32 + 8 * fq;
;                 f32x4 v0 = acc[ai][bj][m][0] * rs, v1 = acc[ai][bj][m][1] * rs;
;                 if (ACT == 1) {
; #pragma unroll
;                     for (int j = 0; j < 4; ++j) { v0[j] = silu_f(v0[j]); v1[j] = silu_f(v1[j]); } }
;                 if (ACT == 2) {
; #pragma unroll
;                     for (int j = 0; j < 4; ++j) { v0[j] = sigmoid_f(v0[j]); v1[j] = sigmoid_f(v1[j]); } }
;                 __builtin_nontemporal_store(pack8(v0, v1), (u32x4*)(P + (size_t)row * NCO + col));
;             }
	v_exp_f32_e32 v171, v171
	v_exp_f32_e32 v172, v172
	v_exp_f32_e32 v173, v173
	v_exp_f32_e32 v174, v174
	v_exp_f32_e32 v175, v175
	v_pk_add_f32 v[168:169], v[168:169], 1.0 op_sel_hi:[1,0]
	v_pk_add_f32 v[170:171], v[170:171], 1.0 op_sel_hi:[1,0]
	v_pk_add_f32 v[172:173], v[172:173], 1.0 op_sel_hi:[1,0]
	v_pk_add_f32 v[174:175], v[174:175], 1.0 op_sel_hi:[1,0]
	v_rcp_f32_e32 v168, v168
	v_rcp_f32_e32 v169, v169
	v_rcp_f32_e32 v170, v170
	v_rcp_f32_e32 v171, v171
	v_rcp_f32_e32 v172, v172
	v_rcp_f32_e32 v173, v173
	v_rcp_f32_e32 v174, v174
	v_rcp_f32_e32 v175, v175
	v_pk_mul_f32 v[98:99], v[98:99], v[168:169]
	v_pk_mul_f32 v[100:101], v[100:101], v[170:171]
	v_pk_mul_f32 v[90:91], v[90:91], v[172:173]
	v_pk_mul_f32 v[92:93], v[92:93], v[174:175]
	v_cvt_pk_bf16_f32 v180, v98, v99
	v_cvt_pk_bf16_f32 v181, v100, v101
	v_cvt_pk_bf16_f32 v182, v90, v91
	v_cvt_pk_bf16_f32 v183, v92, v93
	global_store_dwordx4 v[236:237], v[180:183], off offset:256 nt
	v_mad_i64_i32 v[234:235], s[4:5], v208, s33, v[232:233]
	v_pk_mul_f32 v[102:103], v[102:103], v[152:153] op_sel_hi:[1,0]
	v_pk_mul_f32 v[104:105], v[104:105], v[152:153] op_sel_hi:[1,0]
	v_pk_mul_f32 v[94:95], v[94:95], v[152:153] op_sel_hi:[1,0]
	v_pk_mul_f32 v[96:97], v[96:97], v[152:153] op_sel_hi:[1,0]
	v_pk_mul_f32 v[168:169], v[102:103], s[98:99] op_sel_hi:[1,0]
	v_pk_mul_f32 v[170:171], v[104:105], s[98:99] op_sel_hi:[1,0]
	v_pk_mul_f32 v[172:173], v[94:95], s[98:99] op_sel_hi:[1,0]
	v_pk_mul_f32 v[174:175], v[96:97], s[98:99] op_sel_hi:[1,0]
	v_exp_f32_e32 v168, v168
	v_exp_f32_e32 v169, v169
	v_exp_f32_e32 v170, v170
	v_exp_f32_e32 v171, v171
	v_exp_f32_e32 v172, v172
	v_exp_f32_e32 v173, v173
	v_exp_f32_e32 v174, v174
	v_exp_f32_e32 v175, v175
	v_pk_add_f32 v[168:169], v[168:169], 1.0 op_sel_hi:[1,0]
	v_pk_add_f32 v[170:171], v[170:171], 1.0 op_sel_hi:[1,0]
	v_pk_add_f32 v[172:173], v[172:173], 1.0 op_sel_hi:[1,0]
	v_pk_add_f32 v[174:175], v[174:175], 1.0 op_sel_hi:[1,0]
	v_rcp_f32_e32 v168, v168
	v_rcp_f32_e32 v169, v169
	v_rcp_f32_e32 v170, v170
	v_rcp_f32_e32 v171, v171
	v_rcp_f32_e32 v172, v172
	v_rcp_f32_e32 v173, v173
	v_rcp_f32_e32 v174, v174
	v_rcp_f32_e32 v175, v175
	v_pk_mul_f32 v[102:103], v[102:103], v[168:169]
	v_pk_mul_f32 v[104:105], v[104:105], v[170:171]
	v_pk_mul_f32 v[94:95], v[94:95], v[172:173]
	v_pk_mul_f32 v[96:97], v[96:97], v[174:175]
	v_cvt_pk_bf16_f32 v176, v102, v103
	v_cvt_pk_bf16_f32 v177, v104, v105
	v_cvt_pk_bf16_f32 v178, v94, v95
	v_cvt_pk_bf16_f32 v179, v96, v97
	global_store_dwordx4 v[234:235], v[176:179], off nt
	v_pk_mul_f32 v[82:83], v[82:83], v[152:153] op_sel_hi:[1,0]
	v_pk_mul_f32 v[84:85], v[84:85], v[152:153] op_sel_hi:[1,0]
	v_pk_mul_f32 v[74:75], v[74:75], v[152:153] op_sel_hi:[1,0]
	v_pk_mul_f32 v[76:77], v[76:77], v[152:153] op_sel_hi:[1,0]
	v_pk_mul_f32 v[168:169], v[82:83], s[98:99] op_sel_hi:[1,0]
	v_pk_mul_f32 v[170:171], v[84:85], s[98:99] op_sel_hi:[1,0]
	v_pk_mul_f32 v[172:173], v[74:75], s[98:99] op_sel_hi:[1,0]
	v_pk_mul_f32 v[174:175], v[76:77], s[98:99] op_sel_hi:[1,0]
	v_exp_f32_e32 v168, v168
	v_exp_f32_e32 v169, v169
	v_exp_f32_e32 v170, v170
	v_exp_f32_e32 v171, v171
	v_exp_f32_e32 v172, v172
	v_exp_f32_e32 v173, v173
	v_exp_f32_e32 v174, v174
	v_exp_f32_e32 v175, v175
	v_pk_add_f32 v[168:169], v[168:169], 1.0 op_sel_hi:[1,0]
	v_pk_add_f32 v[170:171], v[170:171], 1.0 op_sel_hi:[1,0]
	v_pk_add_f32 v[172:173], v[172:173], 1.0 op_sel_hi:[1,0]
	v_pk_add_f32 v[174:175], v[174:175], 1.0 op_sel_hi:[1,0]
	v_rcp_f32_e32 v168, v168
	v_rcp_f32_e32 v169, v169
	v_rcp_f32_e32 v170, v170
	v_rcp_f32_e32 v171, v171
	v_rcp_f32_e32 v172, v172
	v_rcp_f32_e32 v173, v173
	v_rcp_f32_e32 v174, v174
	v_rcp_f32_e32 v175, v175
	v_pk_mul_f32 v[82:83], v[82:83], v[168:169]
	v_pk_mul_f32 v[84:85], v[84:85], v[170:171]
	v_pk_mul_f32 v[74:75], v[74:75], v[172:173]
	v_pk_mul_f32 v[76:77], v[76:77], v[174:175]
	v_cvt_pk_bf16_f32 v180, v82, v83
	v_cvt_pk_bf16_f32 v181, v84, v85
	v_cvt_pk_bf16_f32 v182, v74, v75
	v_cvt_pk_bf16_f32 v183, v76, v77
	global_store_dwordx4 v[234:235], v[180:183], off offset:256 nt
	v_mad_i64_i32 v[236:237], s[4:5], v157, s33, v[232:233]
	v_pk_mul_f32 v[86:87], v[86:87], v[150:151] op_sel_hi:[1,0]
	v_pk_mul_f32 v[88:89], v[88:89], v[150:151] op_sel_hi:[1,0]
	v_pk_mul_f32 v[78:79], v[78:79], v[150:151] op_sel_hi:[1,0]
	v_pk_mul_f32 v[80:81], v[80:81], v[150:151] op_sel_hi:[1,0]
	v_pk_mul_f32 v[168:169], v[86:87], s[98:99] op_sel_hi:[1,0]
	v_pk_mul_f32 v[170:171], v[88:89], s[98:99] op_sel_hi:[1,0]
	v_pk_mul_f32 v[172:173], v[78:79], s[98:99] op_sel_hi:[1,0]
	v_pk_mul_f32 v[174:175], v[80:81], s[98:99] op_sel_hi:[1,0]
	v_exp_f32_e32 v168, v168
	v_exp_f32_e32 v169, v169
	v_exp_f32_e32 v170, v170
	v_exp_f32_e32 v171, v171
	v_exp_f32_e32 v172, v172
	v_exp_f32_e32 v173, v173
	v_exp_f32_e32 v174, v174
	v_exp_f32_e32 v175, v175
	v_pk_add_f32 v[168:169], v[168:169], 1.0 op_sel_hi:[1,0]
	v_pk_add_f32 v[170:171], v[170:171], 1.0 op_sel_hi:[1,0]
	v_pk_add_f32 v[172:173], v[172:173], 1.0 op_sel_hi:[1,0]
	v_pk_add_f32 v[174:175], v[174:175], 1.0 op_sel_hi:[1,0]
	v_rcp_f32_e32 v168, v168
	v_rcp_f32_e32 v169, v169
	v_rcp_f32_e32 v170, v170
	v_rcp_f32_e32 v171, v171
	v_rcp_f32_e32 v172, v172
	v_rcp_f32_e32 v173, v173
	v_rcp_f32_e32 v174, v174
	v_rcp_f32_e32 v175, v175
	v_pk_mul_f32 v[86:87], v[86:87], v[168:169]
	v_pk_mul_f32 v[88:89], v[88:89], v[170:171]
	v_pk_mul_f32 v[78:79], v[78:79], v[172:173]
	v_pk_mul_f32 v[80:81], v[80:81], v[174:175]
	v_cvt_pk_bf16_f32 v176, v86, v87
	v_cvt_pk_bf16_f32 v177, v88, v89
	v_cvt_pk_bf16_f32 v178, v78, v79
	v_cvt_pk_bf16_f32 v179, v80, v81
	global_store_dwordx4 v[236:237], v[176:179], off nt
; __device__ __forceinline__ float sigmoid_f(float x) { return __builtin_amdgcn_rcpf(1.0f + __builtin_amdgcn_exp2f(-1.4426950409f * x)); }
; __device__ __forceinline__ float silu_f(float x) { return x * sigmoid_f(x); }
; __device__ __forceinline__ u32x4 pack8(f32x4 a, f32x4 b) { u32x4 w; w.x = cvt_pk_bf16(a[0], a[1]); w.y = cvt_pk_bf16(a[2], a[3]); w.z = cvt_pk_bf16(b[0], b[1]); w.w = cvt_pk_bf16(b[2], b[3]); return w; }
;     template <int ACT> __device__ __forceinline__ void body(f32x4 (&acc)[2][2][4][2], const Unit& u, int wr, int wc, int fr, int fq, int obase, const float (&rsv)[2][4]) const {
;     ...
;             for (int bj = 0; bj < 2; ++bj) { const int col = obase + bj * 128 + wc * 32 + 8 * fq;
;                 f32x4 v0 = acc[ai][bj][m][0] * rs, v1 = acc[ai][bj][m][1] * rs;
;                 if (ACT == 1) {
; #pragma unroll
;                     for (int j = 0; j < 4; ++j) { v0[j] = silu_f(v0[j]); v1[j] = silu_f(v1[j]); } }
;                 if (ACT == 2) {
; #pragma unroll
;                     for (int j = 0; j < 4; ++j) { v0[j] = sigmoid_f(v0[j]); v1[j] = sigmoid_f(v1[j]); } }
;                 __builtin_nontemporal_store(pack8(v0, v1), (u32x4*)(P + (size_t)row * NCO + col));
;             }
	v_pk_mul_f32 v[70:71], v[70:71], v[150:151] op_sel_hi:[1,0]
	v_pk_mul_f32 v[72:73], v[72:73], v[150:151] op_sel_hi:[1,0]
	v_pk_mul_f32 v[66:67], v[66:67], v[150:151] op_sel_hi:[1,0]
	v_pk_mul_f32 v[68:69], v[68:69], v[150:151] op_sel_hi:[1,0]
	v_pk_mul_f32 v[168:169], v[70:71], s[98:99] op_sel_hi:[1,0]
	v_pk_mul_f32 v[170:171], v[72:73], s[98:99] op_sel_hi:[1,0]
	v_pk_mul_f32 v[172:173], v[66:67], s[98:99] op_sel_hi:[1,0]
	v_pk_mul_f32 v[174:175], v[68:69], s[98:99] op_sel_hi:[1,0]
	v_exp_f32_e32 v168, v168
	v_exp_f32_e32 v169, v169
	v_exp_f32_e32 v170, v170
	v_exp_f32_e32 v171, v171
	v_exp_f32_e32 v172, v172
	v_exp_f32_e32 v173, v173
	v_exp_f32_e32 v174, v174
	v_exp_f32_e32 v175, v175
	v_pk_add_f32 v[168:169], v[168:169], 1.0 op_sel_hi:[1,0]
	v_pk_add_f32 v[170:171], v[170:171], 1.0 op_sel_hi:[1,0]
	v_pk_add_f32 v[172:173], v[172:173], 1.0 op_sel_hi:[1,0]
	v_pk_add_f32 v[174:175], v[174:175], 1.0 op_sel_hi:[1,0]
	v_rcp_f32_e32 v168, v168
	v_rcp_f32_e32 v169, v169
	v_rcp_f32_e32 v170, v170
	v_rcp_f32_e32 v171, v171
	v_rcp_f32_e32 v172, v172
	v_rcp_f32_e32 v173, v173
	v_rcp_f32_e32 v174, v174
	v_rcp_f32_e32 v175, v175
	v_pk_mul_f32 v[70:71], v[70:71], v[168:169]
	v_pk_mul_f32 v[72:73], v[72:73], v[170:171]
	v_pk_mul_f32 v[66:67], v[66:67], v[172:173]
	v_pk_mul_f32 v[68:69], v[68:69], v[174:175]
	v_cvt_pk_bf16_f32 v180, v70, v71
	v_cvt_pk_bf16_f32 v181, v72, v73
	v_cvt_pk_bf16_f32 v182, v66, v67
	v_cvt_pk_bf16_f32 v183, v68, v69
	global_store_dwordx4 v[236:237], v[180:183], off offset:256 nt
	v_mad_i64_i32 v[234:235], s[4:5], v155, s33, v[232:233]
	v_pk_mul_f32 v[62:63], v[62:63], v[148:149] op_sel_hi:[1,0]
	v_pk_mul_f32 v[64:65], v[64:65], v[148:149] op_sel_hi:[1,0]
	v_pk_mul_f32 v[58:59], v[58:59], v[148:149] op_sel_hi:[1,0]
	v_pk_mul_f32 v[60:61], v[60:61], v[148:149] op_sel_hi:[1,0]
	v_pk_mul_f32 v[168:169], v[62:63], s[98:99] op_sel_hi:[1,0]
	v_pk_mul_f32 v[170:171], v[64:65], s[98:99] op_sel_hi:[1,0]
	v_pk_mul_f32 v[172:173], v[58:59], s[98:99] op_sel_hi:[1,0]
	v_pk_mul_f32 v[174:175], v[60:61], s[98:99] op_sel_hi:[1,0]
	v_exp_f32_e32 v168, v168
	v_exp_f32_e32 v169, v169
	v_exp_f32_e32 v170, v170
	v_exp_f32_e32 v171, v171
	v_exp_f32_e32 v172, v172
	v_exp_f32_e32 v173, v173
	v_exp_f32_e32 v174, v174
	v_exp_f32_e32 v175, v175
	v_pk_add_f32 v[168:169], v[168:169], 1.0 op_sel_hi:[1,0]
	v_pk_add_f32 v[170:171], v[170:171], 1.0 op_sel_hi:[1,0]
	v_pk_add_f32 v[172:173], v[172:173], 1.0 op_sel_hi:[1,0]
	v_pk_add_f32 v[174:175], v[174:175], 1.0 op_sel_hi:[1,0]
	v_rcp_f32_e32 v168, v168
	v_rcp_f32_e32 v169, v169
	v_rcp_f32_e32 v170, v170
	v_rcp_f32_e32 v171, v171
	v_rcp_f32_e32 v172, v172
	v_rcp_f32_e32 v173, v173
	v_rcp_f32_e32 v174, v174
	v_rcp_f32_e32 v175, v175
	v_pk_mul_f32 v[62:63], v[62:63], v[168:169]
	v_pk_mul_f32 v[64:65], v[64:65], v[170:171]
	v_pk_mul_f32 v[58:59], v[58:59], v[172:173]
	v_pk_mul_f32 v[60:61], v[60:61], v[174:175]
	v_cvt_pk_bf16_f32 v176, v62, v63
	v_cvt_pk_bf16_f32 v177, v64, v65
	v_cvt_pk_bf16_f32 v178, v58, v59
	v_cvt_pk_bf16_f32 v179, v60, v61
	global_store_dwordx4 v[234:235], v[176:179], off nt
	v_pk_mul_f32 v[50:51], v[50:51], v[148:149] op_sel_hi:[1,0]
	v_pk_mul_f32 v[52:53], v[52:53], v[148:149] op_sel_hi:[1,0]
	v_pk_mul_f32 v[42:43], v[42:43], v[148:149] op_sel_hi:[1,0]
	v_pk_mul_f32 v[44:45], v[44:45], v[148:149] op_sel_hi:[1,0]
	v_pk_mul_f32 v[168:169], v[50:51], s[98:99] op_sel_hi:[1,0]
	v_pk_mul_f32 v[170:171], v[52:53], s[98:99] op_sel_hi:[1,0]
	v_pk_mul_f32 v[172:173], v[42:43], s[98:99] op_sel_hi:[1,0]
	v_pk_mul_f32 v[174:175], v[44:45], s[98:99] op_sel_hi:[1,0]
	v_exp_f32_e32 v168, v168
	v_exp_f32_e32 v169, v169
	v_exp_f32_e32 v170, v170
	v_exp_f32_e32 v171, v171
	v_exp_f32_e32 v172, v172
	v_exp_f32_e32 v173, v173
	v_exp_f32_e32 v174, v174
	v_exp_f32_e32 v175, v175
	v_pk_add_f32 v[168:169], v[168:169], 1.0 op_sel_hi:[1,0]
	v_pk_add_f32 v[170:171], v[170:171], 1.0 op_sel_hi:[1,0]
	v_pk_add_f32 v[172:173], v[172:173], 1.0 op_sel_hi:[1,0]
	v_pk_add_f32 v[174:175], v[174:175], 1.0 op_sel_hi:[1,0]
	v_rcp_f32_e32 v168, v168
	v_rcp_f32_e32 v169, v169
	v_rcp_f32_e32 v170, v170
	v_rcp_f32_e32 v171, v171
	v_rcp_f32_e32 v172, v172
	v_rcp_f32_e32 v173, v173
	v_rcp_f32_e32 v174, v174
	v_rcp_f32_e32 v175, v175
	v_pk_mul_f32 v[50:51], v[50:51], v[168:169]
	v_pk_mul_f32 v[52:53], v[52:53], v[170:171]
	v_pk_mul_f32 v[42:43], v[42:43], v[172:173]
	v_pk_mul_f32 v[44:45], v[44:45], v[174:175]
	v_cvt_pk_bf16_f32 v180, v50, v51
	v_cvt_pk_bf16_f32 v181, v52, v53
	v_cvt_pk_bf16_f32 v182, v42, v43
	v_cvt_pk_bf16_f32 v183, v44, v45
	global_store_dwordx4 v[234:235], v[180:183], off offset:256 nt
	v_mad_i64_i32 v[236:237], s[4:5], v153, s33, v[232:233]
	v_pk_mul_f32 v[54:55], v[54:55], v[146:147] op_sel_hi:[1,0]
	v_pk_mul_f32 v[56:57], v[56:57], v[146:147] op_sel_hi:[1,0]
	v_pk_mul_f32 v[46:47], v[46:47], v[146:147] op_sel_hi:[1,0]
	v_pk_mul_f32 v[48:49], v[48:49], v[146:147] op_sel_hi:[1,0]
	v_pk_mul_f32 v[168:169], v[54:55], s[98:99] op_sel_hi:[1,0]
	v_pk_mul_f32 v[170:171], v[56:57], s[98:99] op_sel_hi:[1,0]
	v_pk_mul_f32 v[172:173], v[46:47], s[98:99] op_sel_hi:[1,0]
	v_pk_mul_f32 v[174:175], v[48:49], s[98:99] op_sel_hi:[1,0]
	v_exp_f32_e32 v168, v168
	v_exp_f32_e32 v169, v169
	v_exp_f32_e32 v170, v170
	v_exp_f32_e32 v171, v171
	v_exp_f32_e32 v172, v172
	v_exp_f32_e32 v173, v173
	v_exp_f32_e32 v174, v174
	v_exp_f32_e32 v175, v175
	v_pk_add_f32 v[168:169], v[168:169], 1.0 op_sel_hi:[1,0]
	v_pk_add_f32 v[170:171], v[170:171], 1.0 op_sel_hi:[1,0]
	v_pk_add_f32 v[172:173], v[172:173], 1.0 op_sel_hi:[1,0]
	v_pk_add_f32 v[174:175], v[174:175], 1.0 op_sel_hi:[1,0]
	v_rcp_f32_e32 v168, v168
	v_rcp_f32_e32 v169, v169
; __device__ __forceinline__ float sigmoid_f(float x) { return __builtin_amdgcn_rcpf(1.0f + __builtin_amdgcn_exp2f(-1.4426950409f * x)); }
; __device__ __forceinline__ float silu_f(float x) { return x * sigmoid_f(x); }
; __device__ __forceinline__ u32x4 pack8(f32x4 a, f32x4 b) { u32x4 w; w.x = cvt_pk_bf16(a[0], a[1]); w.y = cvt_pk_bf16(a[2], a[3]); w.z = cvt_pk_bf16(b[0], b[1]); w.w = cvt_pk_bf16(b[2], b[3]); return w; }
;     template <int ACT> __device__ __forceinline__ void body(f32x4 (&acc)[2][2][4][2], const Unit& u, int wr, int wc, int fr, int fq, int obase, const float (&rsv)[2][4]) const {
;     ...
;             for (int bj = 0; bj < 2; ++bj) { const int col = obase + bj * 128 + wc * 32 + 8 * fq;
;                 f32x4 v0 = acc[ai][bj][m][0] * rs, v1 = acc[ai][bj][m][1] * rs;
;                 if (ACT == 1) {
; #pragma unroll
;                     for (int j = 0; j < 4; ++j) { v0[j] = silu_f(v0[j]); v1[j] = silu_f(v1[j]); } }
;                 if (ACT == 2) {
; #pragma unroll
;                     for (int j = 0; j < 4; ++j) { v0[j] = sigmoid_f(v0[j]); v1[j] = sigmoid_f(v1[j]); } }
;                 __builtin_nontemporal_store(pack8(v0, v1), (u32x4*)(P + (size_t)row * NCO + col));
;             }
	v_rcp_f32_e32 v170, v170
	v_rcp_f32_e32 v171, v171
	v_rcp_f32_e32 v172, v172
	v_rcp_f32_e32 v173, v173
	v_rcp_f32_e32 v174, v174
	v_rcp_f32_e32 v175, v175
	v_pk_mul_f32 v[54:55], v[54:55], v[168:169]
	v_pk_mul_f32 v[56:57], v[56:57], v[170:171]
	v_pk_mul_f32 v[46:47], v[46:47], v[172:173]
	v_pk_mul_f32 v[48:49], v[48:49], v[174:175]
	v_cvt_pk_bf16_f32 v176, v54, v55
	v_cvt_pk_bf16_f32 v177, v56, v57
	v_cvt_pk_bf16_f32 v178, v46, v47
	v_cvt_pk_bf16_f32 v179, v48, v49
	global_store_dwordx4 v[236:237], v[176:179], off nt
	v_pk_mul_f32 v[34:35], v[34:35], v[146:147] op_sel_hi:[1,0]
	v_pk_mul_f32 v[36:37], v[36:37], v[146:147] op_sel_hi:[1,0]
	v_pk_mul_f32 v[26:27], v[26:27], v[146:147] op_sel_hi:[1,0]
	v_pk_mul_f32 v[28:29], v[28:29], v[146:147] op_sel_hi:[1,0]
	v_pk_mul_f32 v[168:169], v[34:35], s[98:99] op_sel_hi:[1,0]
	v_pk_mul_f32 v[170:171], v[36:37], s[98:99] op_sel_hi:[1,0]
	v_pk_mul_f32 v[172:173], v[26:27], s[98:99] op_sel_hi:[1,0]
	v_pk_mul_f32 v[174:175], v[28:29], s[98:99] op_sel_hi:[1,0]
	v_exp_f32_e32 v168, v168
	v_exp_f32_e32 v169, v169
	v_exp_f32_e32 v170, v170
	v_exp_f32_e32 v171, v171
	v_exp_f32_e32 v172, v172
	v_exp_f32_e32 v173, v173
	v_exp_f32_e32 v174, v174
	v_exp_f32_e32 v175, v175
	v_pk_add_f32 v[168:169], v[168:169], 1.0 op_sel_hi:[1,0]
	v_pk_add_f32 v[170:171], v[170:171], 1.0 op_sel_hi:[1,0]
	v_pk_add_f32 v[172:173], v[172:173], 1.0 op_sel_hi:[1,0]
	v_pk_add_f32 v[174:175], v[174:175], 1.0 op_sel_hi:[1,0]
	v_rcp_f32_e32 v168, v168
	v_rcp_f32_e32 v169, v169
	v_rcp_f32_e32 v170, v170
	v_rcp_f32_e32 v171, v171
	v_rcp_f32_e32 v172, v172
	v_rcp_f32_e32 v173, v173
	v_rcp_f32_e32 v174, v174
	v_rcp_f32_e32 v175, v175
	v_pk_mul_f32 v[34:35], v[34:35], v[168:169]
	v_pk_mul_f32 v[36:37], v[36:37], v[170:171]
	v_pk_mul_f32 v[26:27], v[26:27], v[172:173]
	v_pk_mul_f32 v[28:29], v[28:29], v[174:175]
	v_cvt_pk_bf16_f32 v180, v34, v35
	v_cvt_pk_bf16_f32 v181, v36, v37
	v_cvt_pk_bf16_f32 v182, v26, v27
	v_cvt_pk_bf16_f32 v183, v28, v29
	global_store_dwordx4 v[236:237], v[180:183], off offset:256 nt
	v_mad_i64_i32 v[234:235], s[4:5], v151, s33, v[232:233]
	v_pk_mul_f32 v[38:39], v[38:39], v[144:145] op_sel_hi:[1,0]
	v_pk_mul_f32 v[40:41], v[40:41], v[144:145] op_sel_hi:[1,0]
	v_pk_mul_f32 v[30:31], v[30:31], v[144:145] op_sel_hi:[1,0]
	v_pk_mul_f32 v[32:33], v[32:33], v[144:145] op_sel_hi:[1,0]
	v_pk_mul_f32 v[168:169], v[38:39], s[98:99] op_sel_hi:[1,0]
	v_pk_mul_f32 v[170:171], v[40:41], s[98:99] op_sel_hi:[1,0]
	v_pk_mul_f32 v[172:173], v[30:31], s[98:99] op_sel_hi:[1,0]
	v_pk_mul_f32 v[174:175], v[32:33], s[98:99] op_sel_hi:[1,0]
	v_exp_f32_e32 v168, v168
	v_exp_f32_e32 v169, v169
	v_exp_f32_e32 v170, v170
	v_exp_f32_e32 v171, v171
	v_exp_f32_e32 v172, v172
	v_exp_f32_e32 v173, v173
	v_exp_f32_e32 v174, v174
	v_exp_f32_e32 v175, v175
	v_pk_add_f32 v[168:169], v[168:169], 1.0 op_sel_hi:[1,0]
	v_pk_add_f32 v[170:171], v[170:171], 1.0 op_sel_hi:[1,0]
	v_pk_add_f32 v[172:173], v[172:173], 1.0 op_sel_hi:[1,0]
	v_pk_add_f32 v[174:175], v[174:175], 1.0 op_sel_hi:[1,0]
	v_rcp_f32_e32 v168, v168
	v_rcp_f32_e32 v169, v169
	v_rcp_f32_e32 v170, v170
	v_rcp_f32_e32 v171, v171
	v_rcp_f32_e32 v172, v172
	v_rcp_f32_e32 v173, v173
	v_rcp_f32_e32 v174, v174
	v_rcp_f32_e32 v175, v175
	v_pk_mul_f32 v[38:39], v[38:39], v[168:169]
	v_pk_mul_f32 v[40:41], v[40:41], v[170:171]
	v_pk_mul_f32 v[30:31], v[30:31], v[172:173]
	v_pk_mul_f32 v[32:33], v[32:33], v[174:175]
	v_cvt_pk_bf16_f32 v176, v38, v39
	v_cvt_pk_bf16_f32 v177, v40, v41
	v_cvt_pk_bf16_f32 v178, v30, v31
	v_cvt_pk_bf16_f32 v179, v32, v33
	global_store_dwordx4 v[234:235], v[176:179], off nt
	v_pk_mul_f32 v[18:19], v[18:19], v[144:145] op_sel_hi:[1,0]
	v_pk_mul_f32 v[20:21], v[20:21], v[144:145] op_sel_hi:[1,0]
	v_pk_mul_f32 v[10:11], v[10:11], v[144:145] op_sel_hi:[1,0]
	v_pk_mul_f32 v[12:13], v[12:13], v[144:145] op_sel_hi:[1,0]
	v_pk_mul_f32 v[168:169], v[18:19], s[98:99] op_sel_hi:[1,0]
	v_pk_mul_f32 v[170:171], v[20:21], s[98:99] op_sel_hi:[1,0]
	v_pk_mul_f32 v[172:173], v[10:11], s[98:99] op_sel_hi:[1,0]
	v_pk_mul_f32 v[174:175], v[12:13], s[98:99] op_sel_hi:[1,0]
; __device__ __forceinline__ float sigmoid_f(float x) { return __builtin_amdgcn_rcpf(1.0f + __builtin_amdgcn_exp2f(-1.4426950409f * x)); }
; __device__ __forceinline__ float silu_f(float x) { return x * sigmoid_f(x); }
; __device__ __forceinline__ u32x4 pack8(f32x4 a, f32x4 b) { u32x4 w; w.x = cvt_pk_bf16(a[0], a[1]); w.y = cvt_pk_bf16(a[2], a[3]); w.z = cvt_pk_bf16(b[0], b[1]); w.w = cvt_pk_bf16(b[2], b[3]); return w; }
;     template <int ACT> __device__ __forceinline__ void body(f32x4 (&acc)[2][2][4][2], const Unit& u, int wr, int wc, int fr, int fq, int obase, const float (&rsv)[2][4]) const {
;     ...
;             for (int bj = 0; bj < 2; ++bj) { const int col = obase + bj * 128 + wc * 32 + 8 * fq;
;                 f32x4 v0 = acc[ai][bj][m][0] * rs, v1 = acc[ai][bj][m][1] * rs;
;                 if (ACT == 1) {
; #pragma unroll
;                     for (int j = 0; j < 4; ++j) { v0[j] = silu_f(v0[j]); v1[j] = silu_f(v1[j]); } }
;                 if (ACT == 2) {
; #pragma unroll
;                     for (int j = 0; j < 4; ++j) { v0[j] = sigmoid_f(v0[j]); v1[j] = sigmoid_f(v1[j]); } }
;                 __builtin_nontemporal_store(pack8(v0, v1), (u32x4*)(P + (size_t)row * NCO + col));
;             }
	v_exp_f32_e32 v168, v168
	v_exp_f32_e32 v169, v169
	v_exp_f32_e32 v170, v170
	v_exp_f32_e32 v171, v171
	v_exp_f32_e32 v172, v172
	v_exp_f32_e32 v173, v173
	v_exp_f32_e32 v174, v174
	v_exp_f32_e32 v175, v175
	v_pk_add_f32 v[168:169], v[168:169], 1.0 op_sel_hi:[1,0]
	v_pk_add_f32 v[170:171], v[170:171], 1.0 op_sel_hi:[1,0]
	v_pk_add_f32 v[172:173], v[172:173], 1.0 op_sel_hi:[1,0]
	v_pk_add_f32 v[174:175], v[174:175], 1.0 op_sel_hi:[1,0]
	v_rcp_f32_e32 v168, v168
	v_rcp_f32_e32 v169, v169
	v_rcp_f32_e32 v170, v170
	v_rcp_f32_e32 v171, v171
	v_rcp_f32_e32 v172, v172
	v_rcp_f32_e32 v173, v173
	v_rcp_f32_e32 v174, v174
	v_rcp_f32_e32 v175, v175
	v_pk_mul_f32 v[18:19], v[18:19], v[168:169]
	v_pk_mul_f32 v[20:21], v[20:21], v[170:171]
	v_pk_mul_f32 v[10:11], v[10:11], v[172:173]
	v_pk_mul_f32 v[12:13], v[12:13], v[174:175]
	v_cvt_pk_bf16_f32 v180, v18, v19
	v_cvt_pk_bf16_f32 v181, v20, v21
	v_cvt_pk_bf16_f32 v182, v10, v11
	v_cvt_pk_bf16_f32 v183, v12, v13
	global_store_dwordx4 v[234:235], v[180:183], off offset:256 nt
	v_mad_i64_i32 v[236:237], s[4:5], v149, s33, v[232:233]
	v_pk_mul_f32 v[22:23], v[22:23], v[142:143] op_sel_hi:[1,0]
	v_pk_mul_f32 v[24:25], v[24:25], v[142:143] op_sel_hi:[1,0]
	v_pk_mul_f32 v[14:15], v[14:15], v[142:143] op_sel_hi:[1,0]
	v_pk_mul_f32 v[16:17], v[16:17], v[142:143] op_sel_hi:[1,0]
	v_pk_mul_f32 v[168:169], v[22:23], s[98:99] op_sel_hi:[1,0]
	v_pk_mul_f32 v[170:171], v[24:25], s[98:99] op_sel_hi:[1,0]
	v_pk_mul_f32 v[172:173], v[14:15], s[98:99] op_sel_hi:[1,0]
	v_pk_mul_f32 v[174:175], v[16:17], s[98:99] op_sel_hi:[1,0]
	v_exp_f32_e32 v168, v168
	v_exp_f32_e32 v169, v169
	v_exp_f32_e32 v170, v170
	v_exp_f32_e32 v171, v171
	v_exp_f32_e32 v172, v172
	v_exp_f32_e32 v173, v173
	v_exp_f32_e32 v174, v174
	v_exp_f32_e32 v175, v175
	v_pk_add_f32 v[168:169], v[168:169], 1.0 op_sel_hi:[1,0]
	v_pk_add_f32 v[170:171], v[170:171], 1.0 op_sel_hi:[1,0]
	v_pk_add_f32 v[172:173], v[172:173], 1.0 op_sel_hi:[1,0]
	v_pk_add_f32 v[174:175], v[174:175], 1.0 op_sel_hi:[1,0]
	v_rcp_f32_e32 v168, v168
	v_rcp_f32_e32 v169, v169
	v_rcp_f32_e32 v170, v170
	v_rcp_f32_e32 v171, v171
	v_rcp_f32_e32 v172, v172
	v_rcp_f32_e32 v173, v173
	v_rcp_f32_e32 v174, v174
	v_rcp_f32_e32 v175, v175
	v_pk_mul_f32 v[22:23], v[22:23], v[168:169]
	v_pk_mul_f32 v[24:25], v[24:25], v[170:171]
	v_pk_mul_f32 v[14:15], v[14:15], v[172:173]
	v_pk_mul_f32 v[16:17], v[16:17], v[174:175]
	v_cvt_pk_bf16_f32 v176, v22, v23
	v_cvt_pk_bf16_f32 v177, v24, v25
	v_cvt_pk_bf16_f32 v178, v14, v15
	v_cvt_pk_bf16_f32 v179, v16, v17
	global_store_dwordx4 v[236:237], v[176:179], off nt
	v_pk_mul_f32 v[6:7], v[6:7], v[142:143] op_sel_hi:[1,0]
	v_pk_mul_f32 v[8:9], v[8:9], v[142:143] op_sel_hi:[1,0]
	v_pk_mul_f32 v[2:3], v[2:3], v[142:143] op_sel_hi:[1,0]
	v_pk_mul_f32 v[4:5], v[4:5], v[142:143] op_sel_hi:[1,0]
	v_pk_mul_f32 v[168:169], v[6:7], s[98:99] op_sel_hi:[1,0]
	v_pk_mul_f32 v[170:171], v[8:9], s[98:99] op_sel_hi:[1,0]
	v_pk_mul_f32 v[172:173], v[2:3], s[98:99] op_sel_hi:[1,0]
	v_pk_mul_f32 v[174:175], v[4:5], s[98:99] op_sel_hi:[1,0]
	v_exp_f32_e32 v168, v168
	v_exp_f32_e32 v169, v169
	v_exp_f32_e32 v170, v170
	v_exp_f32_e32 v171, v171
	v_exp_f32_e32 v172, v172
	v_exp_f32_e32 v173, v173
	v_exp_f32_e32 v174, v174
	v_exp_f32_e32 v175, v175
	v_pk_add_f32 v[168:169], v[168:169], 1.0 op_sel_hi:[1,0]
	v_pk_add_f32 v[170:171], v[170:171], 1.0 op_sel_hi:[1,0]
	v_pk_add_f32 v[172:173], v[172:173], 1.0 op_sel_hi:[1,0]
	v_pk_add_f32 v[174:175], v[174:175], 1.0 op_sel_hi:[1,0]
	v_rcp_f32_e32 v168, v168
	v_rcp_f32_e32 v169, v169
	v_rcp_f32_e32 v170, v170
	v_rcp_f32_e32 v171, v171
	v_rcp_f32_e32 v172, v172
	v_rcp_f32_e32 v173, v173
	v_rcp_f32_e32 v174, v174
	v_rcp_f32_e32 v175, v175
	v_pk_mul_f32 v[6:7], v[6:7], v[168:169]
	v_pk_mul_f32 v[8:9], v[8:9], v[170:171]
	v_pk_mul_f32 v[2:3], v[2:3], v[172:173]
	v_pk_mul_f32 v[4:5], v[4:5], v[174:175]
	v_cvt_pk_bf16_f32 v180, v6, v7
	v_cvt_pk_bf16_f32 v181, v8, v9
	v_cvt_pk_bf16_f32 v182, v2, v3
	v_cvt_pk_bf16_f32 v183, v4, v5
	global_store_dwordx4 v[236:237], v[180:183], off offset:256 nt

; __device__ __forceinline__ float sigmoid_f(float x) { return __builtin_amdgcn_rcpf(1.0f + __builtin_amdgcn_exp2f(-1.4426950409f * x)); }
; __device__ __forceinline__ float silu_f(float x) { return x * sigmoid_f(x); }
; __device__ __forceinline__ u32x4 pack8(f32x4 a, f32x4 b) { u32x4 w; w.x = cvt_pk_bf16(a[0], a[1]); w.y = cvt_pk_bf16(a[2], a[3]); w.z = cvt_pk_bf16(b[0], b[1]); w.w = cvt_pk_bf16(b[2], b[3]); return w; }
;     template <int ACT> __device__ __forceinline__ void body_pair(f32x4 (&acc)[2][2][4][2], const Unit& u, int wr, int wc, int fr, int fq, int obase, const float (&rsv)[2][4]) const {
;         EPI_ROWS_BEGIN
;             const float rs = rsv[ai][m]; const int col = obase + wc * 32 + 8 * fq;
;             f32x4 a0 = acc[ai][0][m][0] * rs, a1 = acc[ai][0][m][1] * rs, b0 = acc[ai][1][m][0] * rs, b1 = acc[ai][1][m][1] * rs;
;             if (ACT == 1) {
; #pragma unroll
;                 for (int j = 0; j < 4; ++j) { b0[j] = silu_f(b0[j]); b1[j] = silu_f(b1[j]); } }
;             if (ACT == 2) {
; #pragma unroll
;                 for (int j = 0; j < 4; ++j) { b0[j] = sigmoid_f(b0[j]); b1[j] = sigmoid_f(b1[j]); } }
;             __builtin_nontemporal_store(pack8(a0 * b0, a1 * b1), (u32x4*)(P + (size_t)row * NCO + col));
;         EPI_END
.LBB0_218:
	s_andn2_b64 vcc, exec, s[4:5]
	s_cbranch_vccnz .LBB0_220
	s_lshl_b32 s4, s52, 7
	s_or_b32 s4, s4, s89
	s_mov_b32 s98, 0xbfb8aa3b
	v_lshl_add_u32 v228, v143, 3, s4
	v_lshlrev_b32_e32 v228, 1, v228
	v_ashrrev_i32_e32 v229, 31, v228
	v_lshl_add_u64 v[232:233], s[68:69], 0, v[228:229]
	v_mad_i64_i32 v[234:235], s[4:5], v154, s33, v[232:233]
	v_pk_mul_f32 v[118:119], v[118:119], v[158:159] op_sel_hi:[1,0]
	v_pk_mul_f32 v[120:121], v[120:121], v[158:159] op_sel_hi:[1,0]
	v_pk_mul_f32 v[110:111], v[110:111], v[158:159] op_sel_hi:[1,0]
	v_pk_mul_f32 v[112:113], v[112:113], v[158:159] op_sel_hi:[1,0]
	v_pk_mul_f32 v[168:169], v[118:119], s[98:99] op_sel_hi:[1,0]
	v_pk_mul_f32 v[170:171], v[120:121], s[98:99] op_sel_hi:[1,0]
	v_pk_mul_f32 v[172:173], v[110:111], s[98:99] op_sel_hi:[1,0]
	v_pk_mul_f32 v[174:175], v[112:113], s[98:99] op_sel_hi:[1,0]
	v_exp_f32_e32 v168, v168
	v_exp_f32_e32 v169, v169
	v_exp_f32_e32 v170, v170
	v_exp_f32_e32 v171, v171
	v_exp_f32_e32 v172, v172
	v_exp_f32_e32 v173, v173
	v_exp_f32_e32 v174, v174
	v_exp_f32_e32 v175, v175
	v_pk_mul_f32 v[126:127], v[126:127], v[158:159] op_sel_hi:[1,0]
	v_pk_mul_f32 v[128:129], v[128:129], v[158:159] op_sel_hi:[1,0]
	v_pk_mul_f32 v[122:123], v[122:123], v[158:159] op_sel_hi:[1,0]
	v_pk_mul_f32 v[124:125], v[124:125], v[158:159] op_sel_hi:[1,0]
	v_pk_add_f32 v[168:169], v[168:169], 1.0 op_sel_hi:[1,0]
	v_pk_add_f32 v[170:171], v[170:171], 1.0 op_sel_hi:[1,0]
	v_pk_add_f32 v[172:173], v[172:173], 1.0 op_sel_hi:[1,0]
	v_pk_add_f32 v[174:175], v[174:175], 1.0 op_sel_hi:[1,0]
	v_rcp_f32_e32 v168, v168
	v_rcp_f32_e32 v169, v169
	v_rcp_f32_e32 v170, v170
	v_rcp_f32_e32 v171, v171
	v_rcp_f32_e32 v172, v172
	v_rcp_f32_e32 v173, v173
	v_rcp_f32_e32 v174, v174
	v_rcp_f32_e32 v175, v175
	v_pk_mul_f32 v[168:169], v[118:119], v[168:169]
	v_pk_mul_f32 v[170:171], v[120:121], v[170:171]
	v_pk_mul_f32 v[172:173], v[110:111], v[172:173]
	v_pk_mul_f32 v[174:175], v[112:113], v[174:175]
	v_pk_mul_f32 v[126:127], v[126:127], v[168:169]
	v_pk_mul_f32 v[128:129], v[128:129], v[170:171]
	v_pk_mul_f32 v[122:123], v[122:123], v[172:173]
	v_pk_mul_f32 v[124:125], v[124:125], v[174:175]
	v_cvt_pk_bf16_f32 v176, v126, v127
	v_cvt_pk_bf16_f32 v177, v128, v129
	v_cvt_pk_bf16_f32 v178, v122, v123
	v_cvt_pk_bf16_f32 v179, v124, v125
	global_store_dwordx4 v[234:235], v[176:179], off nt
	v_mad_i64_i32 v[236:237], s[4:5], v209, s33, v[232:233]
	v_pk_mul_f32 v[98:99], v[98:99], v[156:157] op_sel_hi:[1,0]
	v_pk_mul_f32 v[100:101], v[100:101], v[156:157] op_sel_hi:[1,0]
	v_pk_mul_f32 v[90:91], v[90:91], v[156:157] op_sel_hi:[1,0]
	v_pk_mul_f32 v[92:93], v[92:93], v[156:157] op_sel_hi:[1,0]
	v_pk_mul_f32 v[168:169], v[98:99], s[98:99] op_sel_hi:[1,0]
	v_pk_mul_f32 v[170:171], v[100:101], s[98:99] op_sel_hi:[1,0]
	v_pk_mul_f32 v[172:173], v[90:91], s[98:99] op_sel_hi:[1,0]
	v_pk_mul_f32 v[174:175], v[92:93], s[98:99] op_sel_hi:[1,0]
	v_exp_f32_e32 v168, v168
	v_exp_f32_e32 v169, v169
	v_exp_f32_e32 v170, v170
	v_exp_f32_e32 v171, v171
	v_exp_f32_e32 v172, v172
	v_exp_f32_e32 v173, v173
	v_exp_f32_e32 v174, v174
	v_exp_f32_e32 v175, v175
	v_pk_mul_f32 v[114:115], v[114:115], v[156:157] op_sel_hi:[1,0]
	v_pk_mul_f32 v[116:117], v[116:117], v[156:157] op_sel_hi:[1,0]
	v_pk_mul_f32 v[106:107], v[106:107], v[156:157] op_sel_hi:[1,0]
	v_pk_mul_f32 v[108:109], v[108:109], v[156:157] op_sel_hi:[1,0]
	v_pk_add_f32 v[168:169], v[168:169], 1.0 op_sel_hi:[1,0]
	v_pk_add_f32 v[170:171], v[170:171], 1.0 op_sel_hi:[1,0]
	v_pk_add_f32 v[172:173], v[172:173], 1.0 op_sel_hi:[1,0]
	v_pk_add_f32 v[174:175], v[174:175], 1.0 op_sel_hi:[1,0]
	v_rcp_f32_e32 v168, v168
	v_rcp_f32_e32 v169, v169
	v_rcp_f32_e32 v170, v170
	v_rcp_f32_e32 v171, v171
	v_rcp_f32_e32 v172, v172
	v_rcp_f32_e32 v173, v173
	v_rcp_f32_e32 v174, v174
	v_rcp_f32_e32 v175, v175
	v_pk_mul_f32 v[168:169], v[98:99], v[168:169]
	v_pk_mul_f32 v[170:171], v[100:101], v[170:171]
	v_pk_mul_f32 v[172:173], v[90:91], v[172:173]
	v_pk_mul_f32 v[174:175], v[92:93], v[174:175]
	v_pk_mul_f32 v[114:115], v[114:115], v[168:169]
	v_pk_mul_f32 v[116:117], v[116:117], v[170:171]
	v_pk_mul_f32 v[106:107], v[106:107], v[172:173]
	v_pk_mul_f32 v[108:109], v[108:109], v[174:175]
	v_cvt_pk_bf16_f32 v180, v114, v115
	v_cvt_pk_bf16_f32 v181, v116, v117
	v_cvt_pk_bf16_f32 v182, v106, v107
	v_cvt_pk_bf16_f32 v183, v108, v109
	global_store_dwordx4 v[236:237], v[180:183], off nt
	v_mad_i64_i32 v[234:235], s[4:5], v208, s33, v[232:233]
	v_pk_mul_f32 v[82:83], v[82:83], v[152:153] op_sel_hi:[1,0]
	v_pk_mul_f32 v[84:85], v[84:85], v[152:153] op_sel_hi:[1,0]
	v_pk_mul_f32 v[74:75], v[74:75], v[152:153] op_sel_hi:[1,0]
	v_pk_mul_f32 v[76:77], v[76:77], v[152:153] op_sel_hi:[1,0]
	v_pk_mul_f32 v[168:169], v[82:83], s[98:99] op_sel_hi:[1,0]
	v_pk_mul_f32 v[170:171], v[84:85], s[98:99] op_sel_hi:[1,0]
	v_pk_mul_f32 v[172:173], v[74:75], s[98:99] op_sel_hi:[1,0]
	v_pk_mul_f32 v[174:175], v[76:77], s[98:99] op_sel_hi:[1,0]
	v_exp_f32_e32 v168, v168
	v_exp_f32_e32 v169, v169
	v_exp_f32_e32 v170, v170
	v_exp_f32_e32 v171, v171
	v_exp_f32_e32 v172, v172
	v_exp_f32_e32 v173, v173
	v_exp_f32_e32 v174, v174
	v_exp_f32_e32 v175, v175
	v_pk_mul_f32 v[102:103], v[102:103], v[152:153] op_sel_hi:[1,0]
	v_pk_mul_f32 v[104:105], v[104:105], v[152:153] op_sel_hi:[1,0]
	v_pk_mul_f32 v[94:95], v[94:95], v[152:153] op_sel_hi:[1,0]
	v_pk_mul_f32 v[96:97], v[96:97], v[152:153] op_sel_hi:[1,0]
	v_pk_add_f32 v[168:169], v[168:169], 1.0 op_sel_hi:[1,0]
	v_pk_add_f32 v[170:171], v[170:171], 1.0 op_sel_hi:[1,0]
	v_pk_add_f32 v[172:173], v[172:173], 1.0 op_sel_hi:[1,0]
	v_pk_add_f32 v[174:175], v[174:175], 1.0 op_sel_hi:[1,0]
; __device__ __forceinline__ float sigmoid_f(float x) { return __builtin_amdgcn_rcpf(1.0f + __builtin_amdgcn_exp2f(-1.4426950409f * x)); }
; __device__ __forceinline__ float silu_f(float x) { return x * sigmoid_f(x); }
; __device__ __forceinline__ u32x4 pack8(f32x4 a, f32x4 b) { u32x4 w; w.x = cvt_pk_bf16(a[0], a[1]); w.y = cvt_pk_bf16(a[2], a[3]); w.z = cvt_pk_bf16(b[0], b[1]); w.w = cvt_pk_bf16(b[2], b[3]); return w; }
;     template <int ACT> __device__ __forceinline__ void body_pair(f32x4 (&acc)[2][2][4][2], const Unit& u, int wr, int wc, int fr, int fq, int obase, const float (&rsv)[2][4]) const {
;         EPI_ROWS_BEGIN
;             const float rs = rsv[ai][m]; const int col = obase + wc * 32 + 8 * fq;
;             f32x4 a0 = acc[ai][0][m][0] * rs, a1 = acc[ai][0][m][1] * rs, b0 = acc[ai][1][m][0] * rs, b1 = acc[ai][1][m][1] * rs;
;             if (ACT == 1) {
; #pragma unroll
;                 for (int j = 0; j < 4; ++j) { b0[j] = silu_f(b0[j]); b1[j] = silu_f(b1[j]); } }
;             if (ACT == 2) {
; #pragma unroll
;                 for (int j = 0; j < 4; ++j) { b0[j] = sigmoid_f(b0[j]); b1[j] = sigmoid_f(b1[j]); } }
;             __builtin_nontemporal_store(pack8(a0 * b0, a1 * b1), (u32x4*)(P + (size_t)row * NCO + col));
;         EPI_END
	v_rcp_f32_e32 v168, v168
	v_rcp_f32_e32 v169, v169
	v_rcp_f32_e32 v170, v170
	v_rcp_f32_e32 v171, v171
	v_rcp_f32_e32 v172, v172
	v_rcp_f32_e32 v173, v173
	v_rcp_f32_e32 v174, v174
	v_rcp_f32_e32 v175, v175
	v_pk_mul_f32 v[168:169], v[82:83], v[168:169]
	v_pk_mul_f32 v[170:171], v[84:85], v[170:171]
	v_pk_mul_f32 v[172:173], v[74:75], v[172:173]
	v_pk_mul_f32 v[174:175], v[76:77], v[174:175]
	v_pk_mul_f32 v[102:103], v[102:103], v[168:169]
	v_pk_mul_f32 v[104:105], v[104:105], v[170:171]
	v_pk_mul_f32 v[94:95], v[94:95], v[172:173]
	v_pk_mul_f32 v[96:97], v[96:97], v[174:175]
	v_cvt_pk_bf16_f32 v176, v102, v103
	v_cvt_pk_bf16_f32 v177, v104, v105
	v_cvt_pk_bf16_f32 v178, v94, v95
	v_cvt_pk_bf16_f32 v179, v96, v97
	global_store_dwordx4 v[234:235], v[176:179], off nt
	v_mad_i64_i32 v[236:237], s[4:5], v157, s33, v[232:233]
	v_pk_mul_f32 v[70:71], v[70:71], v[150:151] op_sel_hi:[1,0]
	v_pk_mul_f32 v[72:73], v[72:73], v[150:151] op_sel_hi:[1,0]
	v_pk_mul_f32 v[66:67], v[66:67], v[150:151] op_sel_hi:[1,0]
	v_pk_mul_f32 v[68:69], v[68:69], v[150:151] op_sel_hi:[1,0]
	v_pk_mul_f32 v[168:169], v[70:71], s[98:99] op_sel_hi:[1,0]
	v_pk_mul_f32 v[170:171], v[72:73], s[98:99] op_sel_hi:[1,0]
	v_pk_mul_f32 v[172:173], v[66:67], s[98:99] op_sel_hi:[1,0]
	v_pk_mul_f32 v[174:175], v[68:69], s[98:99] op_sel_hi:[1,0]
	v_exp_f32_e32 v168, v168
	v_exp_f32_e32 v169, v169
	v_exp_f32_e32 v170, v170
	v_exp_f32_e32 v171, v171
	v_exp_f32_e32 v172, v172
	v_exp_f32_e32 v173, v173
	v_exp_f32_e32 v174, v174
	v_exp_f32_e32 v175, v175
	v_pk_mul_f32 v[86:87], v[86:87], v[150:151] op_sel_hi:[1,0]
	v_pk_mul_f32 v[88:89], v[88:89], v[150:151] op_sel_hi:[1,0]
	v_pk_mul_f32 v[78:79], v[78:79], v[150:151] op_sel_hi:[1,0]
	v_pk_mul_f32 v[80:81], v[80:81], v[150:151] op_sel_hi:[1,0]
	v_pk_add_f32 v[168:169], v[168:169], 1.0 op_sel_hi:[1,0]
	v_pk_add_f32 v[170:171], v[170:171], 1.0 op_sel_hi:[1,0]
	v_pk_add_f32 v[172:173], v[172:173], 1.0 op_sel_hi:[1,0]
	v_pk_add_f32 v[174:175], v[174:175], 1.0 op_sel_hi:[1,0]
	v_rcp_f32_e32 v168, v168
	v_rcp_f32_e32 v169, v169
	v_rcp_f32_e32 v170, v170
	v_rcp_f32_e32 v171, v171
	v_rcp_f32_e32 v172, v172
	v_rcp_f32_e32 v173, v173
	v_rcp_f32_e32 v174, v174
	v_rcp_f32_e32 v175, v175
	v_pk_mul_f32 v[168:169], v[70:71], v[168:169]
	v_pk_mul_f32 v[170:171], v[72:73], v[170:171]
	v_pk_mul_f32 v[172:173], v[66:67], v[172:173]
	v_pk_mul_f32 v[174:175], v[68:69], v[174:175]
	v_pk_mul_f32 v[86:87], v[86:87], v[168:169]
	v_pk_mul_f32 v[88:89], v[88:89], v[170:171]
	v_pk_mul_f32 v[78:79], v[78:79], v[172:173]
	v_pk_mul_f32 v[80:81], v[80:81], v[174:175]
	v_cvt_pk_bf16_f32 v180, v86, v87
	v_cvt_pk_bf16_f32 v181, v88, v89
	v_cvt_pk_bf16_f32 v182, v78, v79
	v_cvt_pk_bf16_f32 v183, v80, v81
	global_store_dwordx4 v[236:237], v[180:183], off nt
	v_mad_i64_i32 v[234:235], s[4:5], v155, s33, v[232:233]
	v_pk_mul_f32 v[50:51], v[50:51], v[148:149] op_sel_hi:[1,0]
	v_pk_mul_f32 v[52:53], v[52:53], v[148:149] op_sel_hi:[1,0]
	v_pk_mul_f32 v[42:43], v[42:43], v[148:149] op_sel_hi:[1,0]
	v_pk_mul_f32 v[44:45], v[44:45], v[148:149] op_sel_hi:[1,0]
	v_pk_mul_f32 v[168:169], v[50:51], s[98:99] op_sel_hi:[1,0]
	v_pk_mul_f32 v[170:171], v[52:53], s[98:99] op_sel_hi:[1,0]
	v_pk_mul_f32 v[172:173], v[42:43], s[98:99] op_sel_hi:[1,0]
	v_pk_mul_f32 v[174:175], v[44:45], s[98:99] op_sel_hi:[1,0]
	v_exp_f32_e32 v168, v168
	v_exp_f32_e32 v169, v169
	v_exp_f32_e32 v170, v170
	v_exp_f32_e32 v171, v171
	v_exp_f32_e32 v172, v172
	v_exp_f32_e32 v173, v173
	v_exp_f32_e32 v174, v174
	v_exp_f32_e32 v175, v175
	v_pk_mul_f32 v[62:63], v[62:63], v[148:149] op_sel_hi:[1,0]
	v_pk_mul_f32 v[64:65], v[64:65], v[148:149] op_sel_hi:[1,0]
	v_pk_mul_f32 v[58:59], v[58:59], v[148:149] op_sel_hi:[1,0]
	v_pk_mul_f32 v[60:61], v[60:61], v[148:149] op_sel_hi:[1,0]
	v_pk_add_f32 v[168:169], v[168:169], 1.0 op_sel_hi:[1,0]
	v_pk_add_f32 v[170:171], v[170:171], 1.0 op_sel_hi:[1,0]
	v_pk_add_f32 v[172:173], v[172:173], 1.0 op_sel_hi:[1,0]
	v_pk_add_f32 v[174:175], v[174:175], 1.0 op_sel_hi:[1,0]
	v_rcp_f32_e32 v168, v168
	v_rcp_f32_e32 v169, v169
	v_rcp_f32_e32 v170, v170
	v_rcp_f32_e32 v171, v171
	v_rcp_f32_e32 v172, v172
	v_rcp_f32_e32 v173, v173
	v_rcp_f32_e32 v174, v174
	v_rcp_f32_e32 v175, v175
	v_pk_mul_f32 v[168:169], v[50:51], v[168:169]
	v_pk_mul_f32 v[170:171], v[52:53], v[170:171]
	v_pk_mul_f32 v[172:173], v[42:43], v[172:173]
	v_pk_mul_f32 v[174:175], v[44:45], v[174:175]
	v_pk_mul_f32 v[62:63], v[62:63], v[168:169]
	v_pk_mul_f32 v[64:65], v[64:65], v[170:171]
	v_pk_mul_f32 v[58:59], v[58:59], v[172:173]
	v_pk_mul_f32 v[60:61], v[60:61], v[174:175]
	v_cvt_pk_bf16_f32 v176, v62, v63
	v_cvt_pk_bf16_f32 v177, v64, v65
	v_cvt_pk_bf16_f32 v178, v58, v59
	v_cvt_pk_bf16_f32 v179, v60, v61
	global_store_dwordx4 v[234:235], v[176:179], off nt
	v_mad_i64_i32 v[236:237], s[4:5], v153, s33, v[232:233]
	v_pk_mul_f32 v[34:35], v[34:35], v[146:147] op_sel_hi:[1,0]
	v_pk_mul_f32 v[36:37], v[36:37], v[146:147] op_sel_hi:[1,0]
	v_pk_mul_f32 v[26:27], v[26:27], v[146:147] op_sel_hi:[1,0]
	v_pk_mul_f32 v[28:29], v[28:29], v[146:147] op_sel_hi:[1,0]
	v_pk_mul_f32 v[168:169], v[34:35], s[98:99] op_sel_hi:[1,0]
	v_pk_mul_f32 v[170:171], v[36:37], s[98:99] op_sel_hi:[1,0]
	v_pk_mul_f32 v[172:173], v[26:27], s[98:99] op_sel_hi:[1,0]
	v_pk_mul_f32 v[174:175], v[28:29], s[98:99] op_sel_hi:[1,0]
	v_exp_f32_e32 v168, v168
	v_exp_f32_e32 v169, v169
; __device__ __forceinline__ float sigmoid_f(float x) { return __builtin_amdgcn_rcpf(1.0f + __builtin_amdgcn_exp2f(-1.4426950409f * x)); }
; __device__ __forceinline__ float silu_f(float x) { return x * sigmoid_f(x); }
; __device__ __forceinline__ u32x4 pack8(f32x4 a, f32x4 b) { u32x4 w; w.x = cvt_pk_bf16(a[0], a[1]); w.y = cvt_pk_bf16(a[2], a[3]); w.z = cvt_pk_bf16(b[0], b[1]); w.w = cvt_pk_bf16(b[2], b[3]); return w; }
;     template <int ACT> __device__ __forceinline__ void body_pair(f32x4 (&acc)[2][2][4][2], const Unit& u, int wr, int wc, int fr, int fq, int obase, const float (&rsv)[2][4]) const {
;         EPI_ROWS_BEGIN
;             const float rs = rsv[ai][m]; const int col = obase + wc * 32 + 8 * fq;
;             f32x4 a0 = acc[ai][0][m][0] * rs, a1 = acc[ai][0][m][1] * rs, b0 = acc[ai][1][m][0] * rs, b1 = acc[ai][1][m][1] * rs;
;             if (ACT == 1) {
; #pragma unroll
;                 for (int j = 0; j < 4; ++j) { b0[j] = silu_f(b0[j]); b1[j] = silu_f(b1[j]); } }
;             if (ACT == 2) {
; #pragma unroll
;                 for (int j = 0; j < 4; ++j) { b0[j] = sigmoid_f(b0[j]); b1[j] = sigmoid_f(b1[j]); } }
;             __builtin_nontemporal_store(pack8(a0 * b0, a1 * b1), (u32x4*)(P + (size_t)row * NCO + col));
;         EPI_END
	v_exp_f32_e32 v170, v170
	v_exp_f32_e32 v171, v171
	v_exp_f32_e32 v172, v172
	v_exp_f32_e32 v173, v173
	v_exp_f32_e32 v174, v174
	v_exp_f32_e32 v175, v175
	v_pk_mul_f32 v[54:55], v[54:55], v[146:147] op_sel_hi:[1,0]
	v_pk_mul_f32 v[56:57], v[56:57], v[146:147] op_sel_hi:[1,0]
	v_pk_mul_f32 v[46:47], v[46:47], v[146:147] op_sel_hi:[1,0]
	v_pk_mul_f32 v[48:49], v[48:49], v[146:147] op_sel_hi:[1,0]
	v_pk_add_f32 v[168:169], v[168:169], 1.0 op_sel_hi:[1,0]
	v_pk_add_f32 v[170:171], v[170:171], 1.0 op_sel_hi:[1,0]
	v_pk_add_f32 v[172:173], v[172:173], 1.0 op_sel_hi:[1,0]
	v_pk_add_f32 v[174:175], v[174:175], 1.0 op_sel_hi:[1,0]
	v_rcp_f32_e32 v168, v168
	v_rcp_f32_e32 v169, v169
	v_rcp_f32_e32 v170, v170
	v_rcp_f32_e32 v171, v171
	v_rcp_f32_e32 v172, v172
	v_rcp_f32_e32 v173, v173
	v_rcp_f32_e32 v174, v174
	v_rcp_f32_e32 v175, v175
	v_pk_mul_f32 v[168:169], v[34:35], v[168:169]
	v_pk_mul_f32 v[170:171], v[36:37], v[170:171]
	v_pk_mul_f32 v[172:173], v[26:27], v[172:173]
	v_pk_mul_f32 v[174:175], v[28:29], v[174:175]
	v_pk_mul_f32 v[54:55], v[54:55], v[168:169]
	v_pk_mul_f32 v[56:57], v[56:57], v[170:171]
	v_pk_mul_f32 v[46:47], v[46:47], v[172:173]
	v_pk_mul_f32 v[48:49], v[48:49], v[174:175]
	v_cvt_pk_bf16_f32 v180, v54, v55
	v_cvt_pk_bf16_f32 v181, v56, v57
	v_cvt_pk_bf16_f32 v182, v46, v47
	v_cvt_pk_bf16_f32 v183, v48, v49
	global_store_dwordx4 v[236:237], v[180:183], off nt
	v_mad_i64_i32 v[234:235], s[4:5], v151, s33, v[232:233]
	v_pk_mul_f32 v[18:19], v[18:19], v[144:145] op_sel_hi:[1,0]
	v_pk_mul_f32 v[20:21], v[20:21], v[144:145] op_sel_hi:[1,0]
	v_pk_mul_f32 v[10:11], v[10:11], v[144:145] op_sel_hi:[1,0]
	v_pk_mul_f32 v[12:13], v[12:13], v[144:145] op_sel_hi:[1,0]
	v_pk_mul_f32 v[168:169], v[18:19], s[98:99] op_sel_hi:[1,0]
	v_pk_mul_f32 v[170:171], v[20:21], s[98:99] op_sel_hi:[1,0]
	v_pk_mul_f32 v[172:173], v[10:11], s[98:99] op_sel_hi:[1,0]
	v_pk_mul_f32 v[174:175], v[12:13], s[98:99] op_sel_hi:[1,0]
	v_exp_f32_e32 v168, v168
	v_exp_f32_e32 v169, v169
	v_exp_f32_e32 v170, v170
	v_exp_f32_e32 v171, v171
	v_exp_f32_e32 v172, v172
	v_exp_f32_e32 v173, v173
	v_exp_f32_e32 v174, v174
	v_exp_f32_e32 v175, v175
	v_pk_mul_f32 v[38:39], v[38:39], v[144:145] op_sel_hi:[1,0]
	v_pk_mul_f32 v[40:41], v[40:41], v[144:145] op_sel_hi:[1,0]
	v_pk_mul_f32 v[30:31], v[30:31], v[144:145] op_sel_hi:[1,0]
	v_pk_mul_f32 v[32:33], v[32:33], v[144:145] op_sel_hi:[1,0]
	v_pk_add_f32 v[168:169], v[168:169], 1.0 op_sel_hi:[1,0]
	v_pk_add_f32 v[170:171], v[170:171], 1.0 op_sel_hi:[1,0]
	v_pk_add_f32 v[172:173], v[172:173], 1.0 op_sel_hi:[1,0]
	v_pk_add_f32 v[174:175], v[174:175], 1.0 op_sel_hi:[1,0]
	v_rcp_f32_e32 v168, v168
	v_rcp_f32_e32 v169, v169
	v_rcp_f32_e32 v170, v170
	v_rcp_f32_e32 v171, v171
	v_rcp_f32_e32 v172, v172
	v_rcp_f32_e32 v173, v173
	v_rcp_f32_e32 v174, v174
	v_rcp_f32_e32 v175, v175
	v_pk_mul_f32 v[168:169], v[18:19], v[168:169]
	v_pk_mul_f32 v[170:171], v[20:21], v[170:171]
	v_pk_mul_f32 v[172:173], v[10:11], v[172:173]
	v_pk_mul_f32 v[174:175], v[12:13], v[174:175]
	v_pk_mul_f32 v[38:39], v[38:39], v[168:169]
	v_pk_mul_f32 v[40:41], v[40:41], v[170:171]
	v_pk_mul_f32 v[30:31], v[30:31], v[172:173]
	v_pk_mul_f32 v[32:33], v[32:33], v[174:175]
	v_cvt_pk_bf16_f32 v176, v38, v39
	v_cvt_pk_bf16_f32 v177, v40, v41
	v_cvt_pk_bf16_f32 v178, v30, v31
	v_cvt_pk_bf16_f32 v179, v32, v33
	global_store_dwordx4 v[234:235], v[176:179], off nt
	v_mad_i64_i32 v[236:237], s[4:5], v149, s33, v[232:233]
	v_pk_mul_f32 v[6:7], v[6:7], v[142:143] op_sel_hi:[1,0]
	v_pk_mul_f32 v[8:9], v[8:9], v[142:143] op_sel_hi:[1,0]
	v_pk_mul_f32 v[2:3], v[2:3], v[142:143] op_sel_hi:[1,0]
	v_pk_mul_f32 v[4:5], v[4:5], v[142:143] op_sel_hi:[1,0]
	v_pk_mul_f32 v[168:169], v[6:7], s[98:99] op_sel_hi:[1,0]
	v_pk_mul_f32 v[170:171], v[8:9], s[98:99] op_sel_hi:[1,0]
	v_pk_mul_f32 v[172:173], v[2:3], s[98:99] op_sel_hi:[1,0]
	v_pk_mul_f32 v[174:175], v[4:5], s[98:99] op_sel_hi:[1,0]
	v_exp_f32_e32 v168, v168
	v_exp_f32_e32 v169, v169
	v_exp_f32_e32 v170, v170
	v_exp_f32_e32 v171, v171
	v_exp_f32_e32 v172, v172
	v_exp_f32_e32 v173, v173
	v_exp_f32_e32 v174, v174
	v_exp_f32_e32 v175, v175
	v_pk_mul_f32 v[22:23], v[22:23], v[142:143] op_sel_hi:[1,0]
	v_pk_mul_f32 v[24:25], v[24:25], v[142:143] op_sel_hi:[1,0]
	v_pk_mul_f32 v[14:15], v[14:15], v[142:143] op_sel_hi:[1,0]
	v_pk_mul_f32 v[16:17], v[16:17], v[142:143] op_sel_hi:[1,0]
	v_pk_add_f32 v[168:169], v[168:169], 1.0 op_sel_hi:[1,0]
	v_pk_add_f32 v[170:171], v[170:171], 1.0 op_sel_hi:[1,0]
	v_pk_add_f32 v[172:173], v[172:173], 1.0 op_sel_hi:[1,0]
	v_pk_add_f32 v[174:175], v[174:175], 1.0 op_sel_hi:[1,0]
	v_rcp_f32_e32 v168, v168
	v_rcp_f32_e32 v169, v169
	v_rcp_f32_e32 v170, v170
	v_rcp_f32_e32 v171, v171
	v_rcp_f32_e32 v172, v172
	v_rcp_f32_e32 v173, v173
	v_rcp_f32_e32 v174, v174
	v_rcp_f32_e32 v175, v175
	v_pk_mul_f32 v[168:169], v[6:7], v[168:169]
	v_pk_mul_f32 v[170:171], v[8:9], v[170:171]
	v_pk_mul_f32 v[172:173], v[2:3], v[172:173]
	v_pk_mul_f32 v[174:175], v[4:5], v[174:175]
	v_pk_mul_f32 v[22:23], v[22:23], v[168:169]
	v_pk_mul_f32 v[24:25], v[24:25], v[170:171]
	v_pk_mul_f32 v[14:15], v[14:15], v[172:173]
	v_pk_mul_f32 v[16:17], v[16:17], v[174:175]
	v_cvt_pk_bf16_f32 v180, v22, v23
	v_cvt_pk_bf16_f32 v181, v24, v25
	v_cvt_pk_bf16_f32 v182, v14, v15
	v_cvt_pk_bf16_f32 v183, v16, v17
	global_store_dwordx4 v[236:237], v[180:183], off nt
